# v62 + write-through (sc1) on P3 scan state stores and P4 GLU-GEMM epilogue stores (last bursts before grid barriers)
# baseline (speedup 1.0000x reference)
; #define LAS __attribute__((address_space(3)))
; __device__ __forceinline__ void hg_scan(Frame& F, bf16* DSO, int sb, int nsb) {
;     ...
;     for (int T0 = sb * 512; T0 < 32 * 4096; T0 += nsb * 512) {
;         const int T = T0 + F.tid, bh = T0 >> 12, e = T & 4095, v = e >> 5, k4 = (e & 31) * 4;
;         v2u x[32];
; #pragma unroll
;         for (int c = 0; c < 32; ++c) x[c] = *(const v2u*)(DSC + ((size_t)(bh * 32 + c) * HD + v) * HD + k4);
; #pragma unroll
;         for (int i = 0; i < 2; ++i) { const int p = F.tid + 512 * i; *(LAS f32x4*)(DL + p * 4) = *(const f32x4*)(DEC + (size_t)bh * 32 * HD + p * 4); }
;         __syncthreads();
.LBB0_610:
	v_add_u32_e32 v2, s3, v0
	s_ashr_i32 s4, s3, 12
	v_bfe_u32 v148, v2, 5, 7
	s_lshl_b32 s6, s4, 5
	v_lshlrev_b32_e32 v2, 8, v148
	s_ashr_i32 s7, s6, 31
	v_lshl_add_u64 v[10:11], v[4:5], 0, v[2:3]
	s_lshl_b64 s[10:11], s[6:7], 15
	v_lshl_add_u64 v[78:79], v[10:11], 0, s[10:11]
	s_or_b32 s10, s6, 1
	s_ashr_i32 s11, s10, 31
	s_lshl_b64 s[10:11], s[10:11], 15
	v_lshl_add_u64 v[82:83], v[10:11], 0, s[10:11]
	s_or_b32 s10, s6, 2
	s_ashr_i32 s11, s10, 31
	s_lshl_b64 s[10:11], s[10:11], 15
	v_lshl_add_u64 v[86:87], v[10:11], 0, s[10:11]
	s_or_b32 s10, s6, 3
	s_ashr_i32 s11, s10, 31
	s_lshl_b64 s[10:11], s[10:11], 15
	v_lshl_add_u64 v[90:91], v[10:11], 0, s[10:11]
	s_or_b32 s10, s6, 4
	s_ashr_i32 s11, s10, 31
	s_lshl_b64 s[10:11], s[10:11], 15
	v_lshl_add_u64 v[94:95], v[10:11], 0, s[10:11]
	s_or_b32 s10, s6, 5
	s_ashr_i32 s11, s10, 31
	s_lshl_b64 s[10:11], s[10:11], 15
	v_lshl_add_u64 v[98:99], v[10:11], 0, s[10:11]
	s_or_b32 s10, s6, 6
	s_ashr_i32 s11, s10, 31
	s_lshl_b64 s[10:11], s[10:11], 15
	v_lshl_add_u64 v[102:103], v[10:11], 0, s[10:11]
	s_or_b32 s10, s6, 7
	s_ashr_i32 s11, s10, 31
	s_lshl_b64 s[10:11], s[10:11], 15
	v_lshl_add_u64 v[106:107], v[10:11], 0, s[10:11]
	s_or_b32 s10, s6, 8
	s_ashr_i32 s11, s10, 31
	s_lshl_b64 s[10:11], s[10:11], 15
	v_lshl_add_u64 v[110:111], v[10:11], 0, s[10:11]
	s_or_b32 s10, s6, 9
	s_ashr_i32 s11, s10, 31
	s_lshl_b64 s[10:11], s[10:11], 15
	v_lshl_add_u64 v[114:115], v[10:11], 0, s[10:11]
	s_or_b32 s10, s6, 10
	s_ashr_i32 s11, s10, 31
	s_lshl_b64 s[10:11], s[10:11], 15
	v_lshl_add_u64 v[118:119], v[10:11], 0, s[10:11]
	s_or_b32 s10, s6, 11
	s_ashr_i32 s11, s10, 31
	s_lshl_b64 s[10:11], s[10:11], 15
	v_lshl_add_u64 v[122:123], v[10:11], 0, s[10:11]
	s_or_b32 s10, s6, 12
	s_ashr_i32 s11, s10, 31
	s_lshl_b64 s[10:11], s[10:11], 15
	v_lshl_add_u64 v[126:127], v[10:11], 0, s[10:11]
	s_or_b32 s10, s6, 13
	s_ashr_i32 s11, s10, 31
	s_lshl_b64 s[10:11], s[10:11], 15
	v_lshl_add_u64 v[130:131], v[10:11], 0, s[10:11]
	s_or_b32 s10, s6, 14
	s_ashr_i32 s11, s10, 31
	s_lshl_b64 s[10:11], s[10:11], 15
	v_lshl_add_u64 v[134:135], v[10:11], 0, s[10:11]
	s_or_b32 s10, s6, 15
	s_ashr_i32 s11, s10, 31
	s_lshl_b64 s[10:11], s[10:11], 15
	v_lshl_add_u64 v[138:139], v[10:11], 0, s[10:11]
	s_or_b32 s10, s6, 16
	s_ashr_i32 s11, s10, 31
	s_lshl_b64 s[10:11], s[10:11], 15
	v_lshl_add_u64 v[142:143], v[10:11], 0, s[10:11]
	s_or_b32 s10, s6, 17
	s_ashr_i32 s11, s10, 31
	s_lshl_b64 s[10:11], s[10:11], 15
	v_lshl_add_u64 v[68:69], v[10:11], 0, s[10:11]
	s_or_b32 s10, s6, 18
	s_ashr_i32 s11, s10, 31
	s_lshl_b64 s[10:11], s[10:11], 15
	v_lshl_add_u64 v[64:65], v[10:11], 0, s[10:11]
	s_or_b32 s10, s6, 19
	s_ashr_i32 s11, s10, 31
	s_lshl_b64 s[10:11], s[10:11], 15
	v_lshl_add_u64 v[60:61], v[10:11], 0, s[10:11]
	s_or_b32 s10, s6, 20
	s_ashr_i32 s11, s10, 31
	s_lshl_b64 s[10:11], s[10:11], 15
	v_lshl_add_u64 v[56:57], v[10:11], 0, s[10:11]
	s_or_b32 s10, s6, 21
	s_ashr_i32 s11, s10, 31
	s_lshl_b64 s[10:11], s[10:11], 15
	v_lshl_add_u64 v[52:53], v[10:11], 0, s[10:11]
	s_or_b32 s10, s6, 22
	s_ashr_i32 s11, s10, 31
	s_lshl_b64 s[10:11], s[10:11], 15
	v_lshl_add_u64 v[48:49], v[10:11], 0, s[10:11]
	s_or_b32 s10, s6, 23
	s_ashr_i32 s11, s10, 31
	s_lshl_b64 s[10:11], s[10:11], 15
	v_lshl_add_u64 v[44:45], v[10:11], 0, s[10:11]
	s_or_b32 s10, s6, 24
	s_ashr_i32 s11, s10, 31
	s_lshl_b64 s[10:11], s[10:11], 15
	v_lshl_add_u64 v[40:41], v[10:11], 0, s[10:11]
	s_or_b32 s10, s6, 25
	s_ashr_i32 s11, s10, 31
	s_lshl_b64 s[10:11], s[10:11], 15
	v_lshl_add_u64 v[36:37], v[10:11], 0, s[10:11]
	s_or_b32 s10, s6, 26
	s_ashr_i32 s11, s10, 31
	s_lshl_b64 s[10:11], s[10:11], 15
	v_lshl_add_u64 v[32:33], v[10:11], 0, s[10:11]
	s_or_b32 s10, s6, 27
	s_ashr_i32 s11, s10, 31
	s_lshl_b64 s[10:11], s[10:11], 15
	v_lshl_add_u64 v[28:29], v[10:11], 0, s[10:11]
	s_or_b32 s10, s6, 28
	s_ashr_i32 s11, s10, 31
	s_lshl_b64 s[10:11], s[10:11], 15
	s_waitcnt vmcnt(0)
	v_lshl_add_u64 v[24:25], v[10:11], 0, s[10:11]
	s_or_b32 s10, s6, 29
	s_ashr_i32 s11, s10, 31
	s_lshl_b64 s[10:11], s[10:11], 15
	v_lshl_add_u64 v[20:21], v[10:11], 0, s[10:11]
	s_or_b32 s10, s6, 30
	s_or_b32 s6, s6, 31
	s_ashr_i32 s7, s6, 31
	s_lshl_b64 s[6:7], s[6:7], 15
	s_ashr_i32 s5, s4, 31
	v_lshl_add_u64 v[12:13], v[10:11], 0, s[6:7]
	s_lshl_b64 s[6:7], s[4:5], 14
	v_lshl_add_u64 v[146:147], v[8:9], 0, s[6:7]
	global_load_dwordx4 v[74:77], v[146:147], off
	global_load_dwordx2 v[80:81], v[78:79], off
	global_load_dwordx2 v[84:85], v[82:83], off
	global_load_dwordx2 v[88:89], v[86:87], off
	global_load_dwordx2 v[92:93], v[90:91], off
	global_load_dwordx2 v[96:97], v[94:95], off
	global_load_dwordx2 v[100:101], v[98:99], off
	global_load_dwordx2 v[104:105], v[102:103], off
	global_load_dwordx2 v[108:109], v[106:107], off
	global_load_dwordx2 v[112:113], v[110:111], off
	global_load_dwordx2 v[116:117], v[114:115], off
	global_load_dwordx2 v[120:121], v[118:119], off
	global_load_dwordx2 v[124:125], v[122:123], off
	global_load_dwordx2 v[128:129], v[126:127], off
	s_ashr_i32 s11, s10, 31
	s_lshl_b64 s[10:11], s[10:11], 15
	v_lshl_add_u64 v[16:17], v[10:11], 0, s[10:11]
	global_load_dwordx2 v[132:133], v[130:131], off
	global_load_dwordx2 v[136:137], v[134:135], off
	global_load_dwordx2 v[140:141], v[138:139], off
	global_load_dwordx2 v[144:145], v[142:143], off
	global_load_dwordx2 v[66:67], v[68:69], off
	global_load_dwordx2 v[62:63], v[64:65], off
	global_load_dwordx2 v[58:59], v[60:61], off
	global_load_dwordx2 v[54:55], v[56:57], off
	global_load_dwordx2 v[50:51], v[52:53], off
	global_load_dwordx2 v[46:47], v[48:49], off
	global_load_dwordx2 v[42:43], v[44:45], off
	global_load_dwordx2 v[38:39], v[40:41], off
	global_load_dwordx2 v[34:35], v[36:37], off
	global_load_dwordx2 v[30:31], v[32:33], off
	global_load_dwordx2 v[26:27], v[28:29], off
	global_load_dwordx2 v[22:23], v[24:25], off
	global_load_dwordx2 v[18:19], v[20:21], off
	global_load_dwordx2 v[14:15], v[16:17], off
	global_load_dwordx2 v[10:11], v[12:13], off
	s_lshl_b64 s[4:5], s[4:5], 16
	v_lshlrev_b32_e32 v2, 2, v148
	s_add_i32 s3, s3, s8
	s_cmp_lt_i32 s3, 0x20000
	s_waitcnt vmcnt(32)
	ds_write_b128 v70, v[74:77]
	v_add_co_u32_e32 v74, vcc, s9, v146
	s_nop 1
	v_addc_co_u32_e32 v75, vcc, 0, v147, vcc
	global_load_dwordx4 v[74:77], v[74:75], off
	s_waitcnt vmcnt(0)
	ds_write_b128 v70, v[74:77] offset:8192
	s_waitcnt lgkmcnt(0)
	s_barrier
; #define LAS __attribute__((address_space(3)))
; __device__ __forceinline__ unsigned pk2(float lo, float hi) { f32x2_t v = {lo, hi}; bf16x2_t h = __builtin_convertvector(v, bf16x2_t); return __builtin_bit_cast(unsigned, h); }
; __device__ __forceinline__ void hg_scan(Frame& F, bf16* DSO, int sb, int nsb) {
;     ...
;         f32x4 S = {0.f, 0.f, 0.f, 0.f};
; #pragma unroll
;         for (int c = 0; c < 32; ++c) { const f32x4 d = *(const LAS f32x4*)(DL + c * HD + k4);
;             v2u o; o.x = pk2(S.x, S.y); o.y = pk2(S.z, S.w); *(v2u*)(DSO + ((size_t)(bh * 32 + c) * HD + v) * HD + k4) = o;
;             S.x = d.x * S.x + bflo(x[c].x); S.y = d.y * S.y + bfhi(x[c].x); S.z = d.z * S.z + bflo(x[c].y); S.w = d.w * S.w + bfhi(x[c].y); }
	ds_read_b128 v[74:77], v71
	global_store_dwordx2 v[78:79], v[72:73], off sc1
	v_lshlrev_b32_e32 v78, 16, v80
	v_and_b32_e32 v79, 0xffff0000, v80
	s_waitcnt lgkmcnt(0)
	v_pk_fma_f32 v[78:79], v[74:75], 0, v[78:79] op_sel_hi:[1,0,1]
	v_lshlrev_b32_e32 v74, 16, v81
	v_and_b32_e32 v75, 0xffff0000, v81
	v_pk_fma_f32 v[80:81], v[76:77], 0, v[74:75] op_sel_hi:[1,0,1]
	ds_read_b128 v[74:77], v71 offset:512
	v_cvt_pk_bf16_f32 v146, v78, v79
	v_cvt_pk_bf16_f32 v147, v80, v81
	global_store_dwordx2 v[82:83], v[146:147], off sc1
	v_lshlrev_b32_e32 v82, 16, v84
	v_and_b32_e32 v83, 0xffff0000, v84
	s_waitcnt lgkmcnt(0)
	v_pk_fma_f32 v[78:79], v[78:79], v[74:75], v[82:83]
	v_lshlrev_b32_e32 v74, 16, v85
	v_and_b32_e32 v75, 0xffff0000, v85
	v_pk_fma_f32 v[80:81], v[80:81], v[76:77], v[74:75]
	ds_read_b128 v[74:77], v71 offset:1024
	v_cvt_pk_bf16_f32 v82, v78, v79
	v_cvt_pk_bf16_f32 v83, v80, v81
	global_store_dwordx2 v[86:87], v[82:83], off sc1
	v_lshlrev_b32_e32 v82, 16, v88
	v_and_b32_e32 v83, 0xffff0000, v88
	s_waitcnt lgkmcnt(0)
	v_pk_fma_f32 v[78:79], v[78:79], v[74:75], v[82:83]
	v_lshlrev_b32_e32 v74, 16, v89
	v_and_b32_e32 v75, 0xffff0000, v89
	v_pk_fma_f32 v[80:81], v[80:81], v[76:77], v[74:75]
	ds_read_b128 v[74:77], v71 offset:1536
	v_cvt_pk_bf16_f32 v82, v78, v79
	v_cvt_pk_bf16_f32 v83, v80, v81
	global_store_dwordx2 v[90:91], v[82:83], off sc1
	v_lshlrev_b32_e32 v82, 16, v92
	v_and_b32_e32 v83, 0xffff0000, v92
	s_waitcnt lgkmcnt(0)
	v_pk_fma_f32 v[78:79], v[78:79], v[74:75], v[82:83]
	v_lshlrev_b32_e32 v74, 16, v93
	v_and_b32_e32 v75, 0xffff0000, v93
	v_pk_fma_f32 v[80:81], v[80:81], v[76:77], v[74:75]
	ds_read_b128 v[74:77], v71 offset:2048
	v_cvt_pk_bf16_f32 v82, v78, v79
	v_cvt_pk_bf16_f32 v83, v80, v81
	global_store_dwordx2 v[94:95], v[82:83], off sc1
	v_lshlrev_b32_e32 v82, 16, v96
	v_and_b32_e32 v83, 0xffff0000, v96
	s_waitcnt lgkmcnt(0)
	v_pk_fma_f32 v[78:79], v[78:79], v[74:75], v[82:83]
	v_lshlrev_b32_e32 v74, 16, v97
	v_and_b32_e32 v75, 0xffff0000, v97
	v_pk_fma_f32 v[80:81], v[80:81], v[76:77], v[74:75]
	ds_read_b128 v[74:77], v71 offset:2560
	v_cvt_pk_bf16_f32 v82, v78, v79
	v_cvt_pk_bf16_f32 v83, v80, v81
	global_store_dwordx2 v[98:99], v[82:83], off sc1
	v_lshlrev_b32_e32 v82, 16, v100
	v_and_b32_e32 v83, 0xffff0000, v100
	s_waitcnt lgkmcnt(0)
	v_pk_fma_f32 v[78:79], v[78:79], v[74:75], v[82:83]
	v_lshlrev_b32_e32 v74, 16, v101
	v_and_b32_e32 v75, 0xffff0000, v101
	v_pk_fma_f32 v[80:81], v[80:81], v[76:77], v[74:75]
	ds_read_b128 v[74:77], v71 offset:3072
	v_cvt_pk_bf16_f32 v82, v78, v79
	v_cvt_pk_bf16_f32 v83, v80, v81
	global_store_dwordx2 v[102:103], v[82:83], off sc1
	v_lshlrev_b32_e32 v82, 16, v104
	v_and_b32_e32 v83, 0xffff0000, v104
	s_waitcnt lgkmcnt(0)
	v_pk_fma_f32 v[78:79], v[78:79], v[74:75], v[82:83]
	v_lshlrev_b32_e32 v74, 16, v105
	v_and_b32_e32 v75, 0xffff0000, v105
	v_pk_fma_f32 v[80:81], v[80:81], v[76:77], v[74:75]
	ds_read_b128 v[74:77], v71 offset:3584
	v_cvt_pk_bf16_f32 v82, v78, v79
	v_cvt_pk_bf16_f32 v83, v80, v81
	global_store_dwordx2 v[106:107], v[82:83], off sc1
	v_lshlrev_b32_e32 v82, 16, v108
	v_and_b32_e32 v83, 0xffff0000, v108
	s_waitcnt lgkmcnt(0)
	v_pk_fma_f32 v[78:79], v[78:79], v[74:75], v[82:83]
	v_lshlrev_b32_e32 v74, 16, v109
	v_and_b32_e32 v75, 0xffff0000, v109
	v_pk_fma_f32 v[80:81], v[80:81], v[76:77], v[74:75]
	ds_read_b128 v[74:77], v71 offset:4096
	v_cvt_pk_bf16_f32 v82, v78, v79
	v_cvt_pk_bf16_f32 v83, v80, v81
	global_store_dwordx2 v[110:111], v[82:83], off sc1
	v_lshlrev_b32_e32 v82, 16, v112
	v_and_b32_e32 v83, 0xffff0000, v112
	s_waitcnt lgkmcnt(0)
	v_pk_fma_f32 v[78:79], v[78:79], v[74:75], v[82:83]
	v_lshlrev_b32_e32 v74, 16, v113
	v_and_b32_e32 v75, 0xffff0000, v113
	v_pk_fma_f32 v[80:81], v[80:81], v[76:77], v[74:75]
	ds_read_b128 v[74:77], v71 offset:4608
	v_cvt_pk_bf16_f32 v82, v78, v79
	v_cvt_pk_bf16_f32 v83, v80, v81
	global_store_dwordx2 v[114:115], v[82:83], off sc1
	v_lshlrev_b32_e32 v82, 16, v116
	v_and_b32_e32 v83, 0xffff0000, v116
	s_waitcnt lgkmcnt(0)
	v_pk_fma_f32 v[78:79], v[78:79], v[74:75], v[82:83]
	v_lshlrev_b32_e32 v74, 16, v117
	v_and_b32_e32 v75, 0xffff0000, v117
	v_pk_fma_f32 v[80:81], v[80:81], v[76:77], v[74:75]
	ds_read_b128 v[74:77], v71 offset:5120
	v_cvt_pk_bf16_f32 v82, v78, v79
	v_cvt_pk_bf16_f32 v83, v80, v81
	global_store_dwordx2 v[118:119], v[82:83], off sc1
	v_lshlrev_b32_e32 v82, 16, v120
	v_and_b32_e32 v83, 0xffff0000, v120
	s_waitcnt lgkmcnt(0)
	v_pk_fma_f32 v[78:79], v[78:79], v[74:75], v[82:83]
	v_lshlrev_b32_e32 v74, 16, v121
	v_and_b32_e32 v75, 0xffff0000, v121
	v_pk_fma_f32 v[80:81], v[80:81], v[76:77], v[74:75]
	ds_read_b128 v[74:77], v71 offset:5632
	v_cvt_pk_bf16_f32 v82, v78, v79
	v_cvt_pk_bf16_f32 v83, v80, v81
	global_store_dwordx2 v[122:123], v[82:83], off sc1
	v_lshlrev_b32_e32 v82, 16, v124
	v_and_b32_e32 v83, 0xffff0000, v124
	s_waitcnt lgkmcnt(0)
	v_pk_fma_f32 v[78:79], v[78:79], v[74:75], v[82:83]
	v_lshlrev_b32_e32 v74, 16, v125
	v_and_b32_e32 v75, 0xffff0000, v125
	v_pk_fma_f32 v[80:81], v[80:81], v[76:77], v[74:75]
	ds_read_b128 v[74:77], v71 offset:6144
	v_cvt_pk_bf16_f32 v82, v78, v79
	v_cvt_pk_bf16_f32 v83, v80, v81
	global_store_dwordx2 v[126:127], v[82:83], off sc1
	v_lshlrev_b32_e32 v82, 16, v128
	v_and_b32_e32 v83, 0xffff0000, v128
	s_waitcnt lgkmcnt(0)
	v_pk_fma_f32 v[78:79], v[78:79], v[74:75], v[82:83]
	v_lshlrev_b32_e32 v74, 16, v129
	v_and_b32_e32 v75, 0xffff0000, v129
	v_pk_fma_f32 v[80:81], v[80:81], v[76:77], v[74:75]
	ds_read_b128 v[74:77], v71 offset:6656
	v_cvt_pk_bf16_f32 v82, v78, v79
	v_cvt_pk_bf16_f32 v83, v80, v81
	global_store_dwordx2 v[130:131], v[82:83], off sc1
	v_lshlrev_b32_e32 v82, 16, v132
	v_and_b32_e32 v83, 0xffff0000, v132
	s_waitcnt lgkmcnt(0)
; #define LAS __attribute__((address_space(3)))
; __device__ __forceinline__ unsigned pk2(float lo, float hi) { f32x2_t v = {lo, hi}; bf16x2_t h = __builtin_convertvector(v, bf16x2_t); return __builtin_bit_cast(unsigned, h); }
; __device__ __forceinline__ void hg_scan(Frame& F, bf16* DSO, int sb, int nsb) {
;     ...
;     for (int T0 = sb * 512; T0 < 32 * 4096; T0 += nsb * 512) {
;         const int T = T0 + F.tid, bh = T0 >> 12, e = T & 4095, v = e >> 5, k4 = (e & 31) * 4;
;         v2u x[32];
; #pragma unroll
;         for (int c = 0; c < 32; ++c) x[c] = *(const v2u*)(DSC + ((size_t)(bh * 32 + c) * HD + v) * HD + k4);
; #pragma unroll
;         for (int i = 0; i < 2; ++i) { const int p = F.tid + 512 * i; *(LAS f32x4*)(DL + p * 4) = *(const f32x4*)(DEC + (size_t)bh * 32 * HD + p * 4); }
;         __syncthreads();
;         f32x4 S = {0.f, 0.f, 0.f, 0.f};
; #pragma unroll
;         for (int c = 0; c < 32; ++c) { const f32x4 d = *(const LAS f32x4*)(DL + c * HD + k4);
;             v2u o; o.x = pk2(S.x, S.y); o.y = pk2(S.z, S.w); *(v2u*)(DSO + ((size_t)(bh * 32 + c) * HD + v) * HD + k4) = o;
;             S.x = d.x * S.x + bflo(x[c].x); S.y = d.y * S.y + bfhi(x[c].x); S.z = d.z * S.z + bflo(x[c].y); S.w = d.w * S.w + bfhi(x[c].y); }
;         float* o = F.out + O_PHG + (size_t)bh * HD * HD + (size_t)k4 * HD + v;
;         o[0] = S.x; o[HD] = S.y; o[2 * HD] = S.z; o[3 * HD] = S.w;
;         __syncthreads();
;     }
	v_pk_fma_f32 v[78:79], v[78:79], v[74:75], v[82:83]
	v_lshlrev_b32_e32 v74, 16, v133
	v_and_b32_e32 v75, 0xffff0000, v133
	v_pk_fma_f32 v[80:81], v[80:81], v[76:77], v[74:75]
	ds_read_b128 v[74:77], v71 offset:7168
	v_cvt_pk_bf16_f32 v82, v78, v79
	v_cvt_pk_bf16_f32 v83, v80, v81
	global_store_dwordx2 v[134:135], v[82:83], off sc1
	v_lshlrev_b32_e32 v82, 16, v136
	v_and_b32_e32 v83, 0xffff0000, v136
	s_waitcnt lgkmcnt(0)
	v_pk_fma_f32 v[78:79], v[78:79], v[74:75], v[82:83]
	v_lshlrev_b32_e32 v74, 16, v137
	v_and_b32_e32 v75, 0xffff0000, v137
	v_pk_fma_f32 v[80:81], v[80:81], v[76:77], v[74:75]
	ds_read_b128 v[74:77], v71 offset:7680
	v_cvt_pk_bf16_f32 v82, v78, v79
	v_cvt_pk_bf16_f32 v83, v80, v81
	global_store_dwordx2 v[138:139], v[82:83], off sc1
	v_lshlrev_b32_e32 v82, 16, v140
	v_and_b32_e32 v83, 0xffff0000, v140
	s_waitcnt lgkmcnt(0)
	v_pk_fma_f32 v[78:79], v[78:79], v[74:75], v[82:83]
	v_lshlrev_b32_e32 v74, 16, v141
	v_and_b32_e32 v75, 0xffff0000, v141
	v_pk_fma_f32 v[80:81], v[80:81], v[76:77], v[74:75]
	ds_read_b128 v[74:77], v71 offset:8192
	v_cvt_pk_bf16_f32 v82, v78, v79
	v_cvt_pk_bf16_f32 v83, v80, v81
	global_store_dwordx2 v[142:143], v[82:83], off sc1
	v_lshlrev_b32_e32 v82, 16, v144
	v_and_b32_e32 v83, 0xffff0000, v144
	s_waitcnt lgkmcnt(0)
	v_pk_fma_f32 v[78:79], v[78:79], v[74:75], v[82:83]
	v_lshlrev_b32_e32 v74, 16, v145
	v_and_b32_e32 v75, 0xffff0000, v145
	v_pk_fma_f32 v[80:81], v[80:81], v[76:77], v[74:75]
	ds_read_b128 v[74:77], v71 offset:8704
	v_cvt_pk_bf16_f32 v82, v78, v79
	v_cvt_pk_bf16_f32 v83, v80, v81
	global_store_dwordx2 v[68:69], v[82:83], off sc1
	v_lshlrev_b32_e32 v68, 16, v66
	v_and_b32_e32 v69, 0xffff0000, v66
	v_lshlrev_b32_e32 v66, 16, v67
	v_and_b32_e32 v67, 0xffff0000, v67
	s_waitcnt lgkmcnt(0)
	v_pk_fma_f32 v[74:75], v[78:79], v[74:75], v[68:69]
	v_pk_fma_f32 v[76:77], v[80:81], v[76:77], v[66:67]
	ds_read_b128 v[66:69], v71 offset:9216
	v_cvt_pk_bf16_f32 v78, v74, v75
	v_cvt_pk_bf16_f32 v79, v76, v77
	global_store_dwordx2 v[64:65], v[78:79], off sc1
	v_lshlrev_b32_e32 v64, 16, v62
	v_and_b32_e32 v65, 0xffff0000, v62
	v_lshlrev_b32_e32 v62, 16, v63
	v_and_b32_e32 v63, 0xffff0000, v63
	s_waitcnt lgkmcnt(0)
	v_pk_fma_f32 v[66:67], v[74:75], v[66:67], v[64:65]
	v_pk_fma_f32 v[68:69], v[76:77], v[68:69], v[62:63]
	ds_read_b128 v[62:65], v71 offset:9728
	v_cvt_pk_bf16_f32 v74, v66, v67
	v_cvt_pk_bf16_f32 v75, v68, v69
	global_store_dwordx2 v[60:61], v[74:75], off sc1
	v_lshlrev_b32_e32 v60, 16, v58
	v_and_b32_e32 v61, 0xffff0000, v58
	v_lshlrev_b32_e32 v58, 16, v59
	v_and_b32_e32 v59, 0xffff0000, v59
	s_waitcnt lgkmcnt(0)
	v_pk_fma_f32 v[62:63], v[66:67], v[62:63], v[60:61]
	v_pk_fma_f32 v[64:65], v[68:69], v[64:65], v[58:59]
	ds_read_b128 v[58:61], v71 offset:10240
	v_cvt_pk_bf16_f32 v66, v62, v63
	v_cvt_pk_bf16_f32 v67, v64, v65
	global_store_dwordx2 v[56:57], v[66:67], off sc1
	v_lshlrev_b32_e32 v56, 16, v54
	v_and_b32_e32 v57, 0xffff0000, v54
	v_lshlrev_b32_e32 v54, 16, v55
	v_and_b32_e32 v55, 0xffff0000, v55
	s_waitcnt lgkmcnt(0)
	v_pk_fma_f32 v[58:59], v[62:63], v[58:59], v[56:57]
	v_pk_fma_f32 v[60:61], v[64:65], v[60:61], v[54:55]
	ds_read_b128 v[54:57], v71 offset:10752
	v_cvt_pk_bf16_f32 v62, v58, v59
	v_cvt_pk_bf16_f32 v63, v60, v61
	global_store_dwordx2 v[52:53], v[62:63], off sc1
	v_lshlrev_b32_e32 v52, 16, v50
	v_and_b32_e32 v53, 0xffff0000, v50
	v_lshlrev_b32_e32 v50, 16, v51
	v_and_b32_e32 v51, 0xffff0000, v51
	s_waitcnt lgkmcnt(0)
	v_pk_fma_f32 v[54:55], v[58:59], v[54:55], v[52:53]
	v_pk_fma_f32 v[56:57], v[60:61], v[56:57], v[50:51]
	ds_read_b128 v[50:53], v71 offset:11264
	v_cvt_pk_bf16_f32 v58, v54, v55
	v_cvt_pk_bf16_f32 v59, v56, v57
	global_store_dwordx2 v[48:49], v[58:59], off sc1
	v_lshlrev_b32_e32 v48, 16, v46
	v_and_b32_e32 v49, 0xffff0000, v46
	v_lshlrev_b32_e32 v46, 16, v47
	v_and_b32_e32 v47, 0xffff0000, v47
	s_waitcnt lgkmcnt(0)
; #define LAS __attribute__((address_space(3)))
; __device__ __forceinline__ unsigned pk2(float lo, float hi) { f32x2_t v = {lo, hi}; bf16x2_t h = __builtin_convertvector(v, bf16x2_t); return __builtin_bit_cast(unsigned, h); }
; __device__ __forceinline__ void hg_scan(Frame& F, bf16* DSO, int sb, int nsb) {
;     ...
;     for (int T0 = sb * 512; T0 < 32 * 4096; T0 += nsb * 512) {
;         const int T = T0 + F.tid, bh = T0 >> 12, e = T & 4095, v = e >> 5, k4 = (e & 31) * 4;
;         v2u x[32];
; #pragma unroll
;         for (int c = 0; c < 32; ++c) x[c] = *(const v2u*)(DSC + ((size_t)(bh * 32 + c) * HD + v) * HD + k4);
; #pragma unroll
;         for (int i = 0; i < 2; ++i) { const int p = F.tid + 512 * i; *(LAS f32x4*)(DL + p * 4) = *(const f32x4*)(DEC + (size_t)bh * 32 * HD + p * 4); }
;         __syncthreads();
;         f32x4 S = {0.f, 0.f, 0.f, 0.f};
; #pragma unroll
;         for (int c = 0; c < 32; ++c) { const f32x4 d = *(const LAS f32x4*)(DL + c * HD + k4);
;             v2u o; o.x = pk2(S.x, S.y); o.y = pk2(S.z, S.w); *(v2u*)(DSO + ((size_t)(bh * 32 + c) * HD + v) * HD + k4) = o;
;             S.x = d.x * S.x + bflo(x[c].x); S.y = d.y * S.y + bfhi(x[c].x); S.z = d.z * S.z + bflo(x[c].y); S.w = d.w * S.w + bfhi(x[c].y); }
;         float* o = F.out + O_PHG + (size_t)bh * HD * HD + (size_t)k4 * HD + v;
;         o[0] = S.x; o[HD] = S.y; o[2 * HD] = S.z; o[3 * HD] = S.w;
;         __syncthreads();
;     }
	v_pk_fma_f32 v[50:51], v[54:55], v[50:51], v[48:49]
	v_pk_fma_f32 v[52:53], v[56:57], v[52:53], v[46:47]
	ds_read_b128 v[46:49], v71 offset:11776
	v_cvt_pk_bf16_f32 v54, v50, v51
	v_cvt_pk_bf16_f32 v55, v52, v53
	global_store_dwordx2 v[44:45], v[54:55], off sc1
	v_lshlrev_b32_e32 v44, 16, v42
	v_and_b32_e32 v45, 0xffff0000, v42
	v_lshlrev_b32_e32 v42, 16, v43
	v_and_b32_e32 v43, 0xffff0000, v43
	s_waitcnt lgkmcnt(0)
	v_pk_fma_f32 v[46:47], v[50:51], v[46:47], v[44:45]
	v_pk_fma_f32 v[48:49], v[52:53], v[48:49], v[42:43]
	ds_read_b128 v[42:45], v71 offset:12288
	v_cvt_pk_bf16_f32 v50, v46, v47
	v_cvt_pk_bf16_f32 v51, v48, v49
	global_store_dwordx2 v[40:41], v[50:51], off sc1
	v_lshlrev_b32_e32 v40, 16, v38
	v_and_b32_e32 v41, 0xffff0000, v38
	v_lshlrev_b32_e32 v38, 16, v39
	v_and_b32_e32 v39, 0xffff0000, v39
	s_waitcnt lgkmcnt(0)
	v_pk_fma_f32 v[42:43], v[46:47], v[42:43], v[40:41]
	v_pk_fma_f32 v[44:45], v[48:49], v[44:45], v[38:39]
	ds_read_b128 v[38:41], v71 offset:12800
	v_cvt_pk_bf16_f32 v46, v42, v43
	v_cvt_pk_bf16_f32 v47, v44, v45
	global_store_dwordx2 v[36:37], v[46:47], off sc1
	v_lshlrev_b32_e32 v36, 16, v34
	v_and_b32_e32 v37, 0xffff0000, v34
	v_lshlrev_b32_e32 v34, 16, v35
	v_and_b32_e32 v35, 0xffff0000, v35
	s_waitcnt lgkmcnt(0)
	v_pk_fma_f32 v[38:39], v[42:43], v[38:39], v[36:37]
	v_pk_fma_f32 v[40:41], v[44:45], v[40:41], v[34:35]
	ds_read_b128 v[34:37], v71 offset:13312
	v_cvt_pk_bf16_f32 v42, v38, v39
	v_cvt_pk_bf16_f32 v43, v40, v41
	global_store_dwordx2 v[32:33], v[42:43], off sc1
	v_lshlrev_b32_e32 v32, 16, v30
	v_and_b32_e32 v33, 0xffff0000, v30
	v_lshlrev_b32_e32 v30, 16, v31
	v_and_b32_e32 v31, 0xffff0000, v31
	s_waitcnt lgkmcnt(0)
	v_pk_fma_f32 v[34:35], v[38:39], v[34:35], v[32:33]
	v_pk_fma_f32 v[36:37], v[40:41], v[36:37], v[30:31]
	ds_read_b128 v[30:33], v71 offset:13824
	v_cvt_pk_bf16_f32 v38, v34, v35
	v_cvt_pk_bf16_f32 v39, v36, v37
	global_store_dwordx2 v[28:29], v[38:39], off sc1
	v_lshlrev_b32_e32 v28, 16, v26
	v_and_b32_e32 v29, 0xffff0000, v26
	v_lshlrev_b32_e32 v26, 16, v27
	v_and_b32_e32 v27, 0xffff0000, v27
	s_waitcnt lgkmcnt(0)
	v_pk_fma_f32 v[30:31], v[34:35], v[30:31], v[28:29]
	v_pk_fma_f32 v[32:33], v[36:37], v[32:33], v[26:27]
	ds_read_b128 v[26:29], v71 offset:14336
	v_cvt_pk_bf16_f32 v34, v30, v31
	v_cvt_pk_bf16_f32 v35, v32, v33
	global_store_dwordx2 v[24:25], v[34:35], off sc1
	v_lshlrev_b32_e32 v24, 16, v22
	v_and_b32_e32 v25, 0xffff0000, v22
	v_lshlrev_b32_e32 v22, 16, v23
	v_and_b32_e32 v23, 0xffff0000, v23
	s_waitcnt lgkmcnt(0)
	v_pk_fma_f32 v[26:27], v[30:31], v[26:27], v[24:25]
	v_pk_fma_f32 v[28:29], v[32:33], v[28:29], v[22:23]
	ds_read_b128 v[22:25], v71 offset:14848
	v_cvt_pk_bf16_f32 v30, v26, v27
	v_cvt_pk_bf16_f32 v31, v28, v29
	global_store_dwordx2 v[20:21], v[30:31], off sc1
	v_lshlrev_b32_e32 v20, 16, v18
	v_and_b32_e32 v21, 0xffff0000, v18
	v_lshlrev_b32_e32 v18, 16, v19
	v_and_b32_e32 v19, 0xffff0000, v19
	s_waitcnt lgkmcnt(0)
	v_pk_fma_f32 v[22:23], v[26:27], v[22:23], v[20:21]
	v_pk_fma_f32 v[24:25], v[28:29], v[24:25], v[18:19]
	ds_read_b128 v[18:21], v71 offset:15360
	v_cvt_pk_bf16_f32 v26, v22, v23
	v_cvt_pk_bf16_f32 v27, v24, v25
	global_store_dwordx2 v[16:17], v[26:27], off sc1
	v_lshlrev_b32_e32 v16, 16, v14
	v_and_b32_e32 v17, 0xffff0000, v14
	v_lshlrev_b32_e32 v14, 16, v15
	v_and_b32_e32 v15, 0xffff0000, v15
	s_waitcnt lgkmcnt(0)
	v_pk_fma_f32 v[18:19], v[22:23], v[18:19], v[16:17]
	v_pk_fma_f32 v[20:21], v[24:25], v[20:21], v[14:15]
	ds_read_b128 v[14:17], v71 offset:15872
	v_cvt_pk_bf16_f32 v22, v18, v19
	v_cvt_pk_bf16_f32 v23, v20, v21
	global_store_dwordx2 v[12:13], v[22:23], off sc1
	v_lshlrev_b32_e32 v12, 16, v10
	v_and_b32_e32 v13, 0xffff0000, v10
	s_waitcnt lgkmcnt(0)
	v_fmac_f32_e32 v12, v18, v14
	v_fmac_f32_e32 v13, v19, v15
	v_lshlrev_b32_e32 v14, 16, v11
	v_and_b32_e32 v15, 0xffff0000, v11
	v_lshl_add_u64 v[10:11], v[6:7], 0, s[4:5]
	v_lshl_add_u64 v[10:11], v[10:11], 0, v[2:3]
	v_fmac_f32_e32 v14, v20, v16
	v_fmac_f32_e32 v15, v21, v17
	global_store_dword v[10:11], v12, off
	global_store_dword v[10:11], v13, off offset:512
	global_store_dword v[10:11], v14, off offset:1024
	global_store_dword v[10:11], v15, off offset:1536
	s_barrier
	s_cbranch_scc1 .LBB0_610

; __device__ __forceinline__ unsigned cvt_pk_bf16(float lo, float hi) { unsigned r; asm volatile("v_cvt_pk_bf16_f32 %0, %1, %2" : "=v"(r) : "v"(lo), "v"(hi)); return r; }
; #define LAS __attribute__((address_space(3)))
; __device__ __forceinline__ float sigmoidf_(float x) { return __builtin_amdgcn_rcpf(1.0f + __builtin_amdgcn_exp2f(-1.4426950408889634f * x)); }
;     __device__ __forceinline__ void operator()(const pg8::f32x4 (&acc)[2][2][4][2], const Unit& u, int wr, int wc, int fr, int fq) const {
;         const int row0 = u.pm * BM + wr * 64, lane = fr + 16 * fq, rr = lane >> 3, sl = lane & 7;
;         LAS unsigned char* W = scr + (wr * 4 + wc) * 2048;
;         const int gcol = u.pn * BM + wc * 32 + 4 * sl;
;         const bf16* gb = GY + ((size_t)(gcol >> 4) * MTOK + row0 + rr) * 16 + (gcol & 15);
;         bf16* ob = MIX + (size_t)(row0 + rr) * DM + gcol;
;         v2u gc[2][2], gn[2][2];
; #pragma unroll
;         for (int bj = 0; bj < 2; ++bj)
; #pragma unroll
;             for (int p = 0; p < 2; ++p) gc[bj][p] = *(const v2u*)(gb + (size_t)bj * 8 * MTOK * 16 + (size_t)(8 * p) * 16);
; #pragma unroll
;         for (int g = 0; g < 8; ++g) { const int ai = g >> 2, m = g & 3, rg = ai * HALF + m * 16;
;             if (g < 7) { const int rgn = ((g + 1) >> 2) * HALF + ((g + 1) & 3) * 16;
; #pragma unroll
;                 for (int bj = 0; bj < 2; ++bj)
; #pragma unroll
;                     for (int p = 0; p < 2; ++p) gn[bj][p] = *(const v2u*)(gb + (size_t)bj * 8 * MTOK * 16 + (size_t)(rgn + 8 * p) * 16); }
; #pragma unroll
;             for (int bj = 0; bj < 2; ++bj) { *(LAS pg8::f32x4*)epi_slot(W, fr, 2 * fq) = acc[ai][bj][m][0]; *(LAS pg8::f32x4*)epi_slot(W, fr, 2 * fq + 1) = acc[ai][bj][m][1];
; #pragma unroll
;                 for (int p = 0; p < 2; ++p) { const pg8::f32x4 a = *(const LAS pg8::f32x4*)epi_slot(W, 8 * p + rr, sl); const v2u gw = gc[bj][p];
;                     v2u w; w.x = cvt_pk_bf16(bflo(gw.x) * sigmoidf_(a[0]), bfhi(gw.x) * sigmoidf_(a[1])); w.y = cvt_pk_bf16(bflo(gw.y) * sigmoidf_(a[2]), bfhi(gw.y) * sigmoidf_(a[3]));
;                     *(v2u*)(ob + (size_t)(rg + 8 * p) * DM + bj * HALF) = w; } }
; #pragma unroll
;             for (int bj = 0; bj < 2; ++bj)
; #pragma unroll
;                 for (int p = 0; p < 2; ++p) gc[bj][p] = gn[bj][p]; }
.LBB0_680:
	s_lshl_b32 s4, s4, 8
	s_add_i32 s4, s4, s43
	v_lshl_or_b32 v164, s33, 8, v156
	s_ashr_i32 s17, s4, 31
	v_ashrrev_i32_e32 v152, 4, v164
	v_mov_b32_e32 v150, s4
	v_mov_b32_e32 v151, s17
	s_movk_i32 s17, 0x4400
	v_mad_i64_i32 v[150:151], s[24:25], v152, s17, v[150:151]
	v_or_b32_e32 v150, v150, v138
	v_lshlrev_b64 v[150:151], 5, v[150:151]
	v_lshl_add_u64 v[152:153], v[140:141], 0, v[150:151]
	global_load_dwordx2 v[166:167], v[152:153], off
	global_load_dwordx2 v[168:169], v[152:153], off offset:256
	s_mov_b32 s17, 0x441000
	v_add_co_u32_e32 v150, vcc, s17, v152
	v_ashrrev_i32_e32 v165, 31, v164
	s_nop 0
	v_addc_co_u32_e32 v151, vcc, 0, v153, vcc
	global_load_dwordx2 v[170:171], v[150:151], off offset:-4096
	ds_write_b128 v160, v[126:129]
	ds_write_b128 v161, v[122:125]
	v_or_b32_e32 v122, s4, v138
	ds_read_b128 v[124:127], v162
	v_ashrrev_i32_e32 v123, 31, v122
	v_lshlrev_b64 v[122:123], 11, v[122:123]
	v_lshl_add_u64 v[122:123], s[8:9], 0, v[122:123]
	s_movk_i32 s17, 0x4000
	v_lshl_add_u64 v[122:123], v[164:165], 1, v[122:123]
	v_add_co_u32_e32 v172, vcc, s17, v122
	s_mov_b32 s19, 0x440000
	s_waitcnt lgkmcnt(0)
	v_mul_f32_e32 v124, 0xbfb8aa3b, v124
	v_addc_co_u32_e32 v173, vcc, 0, v123, vcc
	v_mul_f32_e32 v125, 0xbfb8aa3b, v125
	v_mul_f32_e32 v126, 0xbfb8aa3b, v126
	v_mul_f32_e32 v127, 0xbfb8aa3b, v127
	v_exp_f32_e32 v163, v124
	v_add_co_u32_e32 v124, vcc, s19, v152
	v_exp_f32_e32 v164, v125
	v_exp_f32_e32 v165, v126
	v_exp_f32_e32 v180, v127
	v_addc_co_u32_e32 v125, vcc, 0, v153, vcc
	global_load_dwordx2 v[174:175], v[152:153], off offset:512
	global_load_dwordx2 v[176:177], v[152:153], off offset:768
	global_load_dwordx2 v[178:179], v[124:125], off offset:256
	global_load_dwordx2 v[128:129], v[124:125], off offset:512
	global_load_dwordx2 v[126:127], v[124:125], off offset:768
	v_add_f32_e32 v164, 1.0, v164
	v_add_f32_e32 v165, 1.0, v165
	v_add_f32_e32 v180, 1.0, v180
	v_add_f32_e32 v163, 1.0, v163
	v_rcp_f32_e32 v164, v164
	v_rcp_f32_e32 v165, v165
	v_rcp_f32_e32 v180, v180
	v_rcp_f32_e32 v163, v163
	s_mov_b32 s4, 0x8000
	s_waitcnt vmcnt(0)
	v_lshlrev_b32_e32 v181, 16, v166
	v_and_b32_e32 v166, 0xffff0000, v166
	v_lshlrev_b32_e32 v182, 16, v167
	v_and_b32_e32 v167, 0xffff0000, v167
	v_mul_f32_e32 v164, v164, v166
	v_mul_f32_e32 v165, v165, v182
	v_mul_f32_e32 v166, v180, v167
	v_mul_f32_e32 v163, v163, v181
	v_cvt_pk_bf16_f32 v180, v163, v164
	v_cvt_pk_bf16_f32 v181, v165, v166
	ds_read_b128 v[164:167], v162 offset:1024
	v_lshlrev_b32_e32 v183, 16, v168
	v_and_b32_e32 v168, 0xffff0000, v168
	v_lshlrev_b32_e32 v163, 16, v169
	v_and_b32_e32 v169, 0xffff0000, v169
	s_waitcnt lgkmcnt(0)
	v_mul_f32_e32 v164, 0xbfb8aa3b, v164
	v_mul_f32_e32 v165, 0xbfb8aa3b, v165
	v_mul_f32_e32 v166, 0xbfb8aa3b, v166
	v_mul_f32_e32 v167, 0xbfb8aa3b, v167
	v_exp_f32_e32 v164, v164
	v_exp_f32_e32 v165, v165
	v_exp_f32_e32 v166, v166
	v_exp_f32_e32 v167, v167
	v_add_f32_e32 v164, 1.0, v164
	v_add_f32_e32 v165, 1.0, v165
	v_add_f32_e32 v166, 1.0, v166
	v_add_f32_e32 v167, 1.0, v167
	v_rcp_f32_e32 v164, v164
	v_rcp_f32_e32 v165, v165
	v_rcp_f32_e32 v166, v166
	v_rcp_f32_e32 v167, v167
	v_mul_f32_e32 v164, v164, v183
	v_mul_f32_e32 v165, v165, v168
	global_store_dwordx2 v[122:123], v[180:181], off sc1
	v_mul_f32_e32 v163, v166, v163
	v_mul_f32_e32 v166, v167, v169
	v_cvt_pk_bf16_f32 v164, v164, v165
	v_cvt_pk_bf16_f32 v165, v163, v166
	ds_write_b128 v160, v[118:121]
	ds_write_b128 v161, v[114:117]
	ds_read_b128 v[114:117], v162
	v_lshlrev_b32_e32 v182, 16, v170
	v_and_b32_e32 v118, 0xffff0000, v170
	v_lshlrev_b32_e32 v119, 16, v171
	v_and_b32_e32 v120, 0xffff0000, v171
	s_waitcnt lgkmcnt(0)
	v_mul_f32_e32 v114, 0xbfb8aa3b, v114
	v_mul_f32_e32 v115, 0xbfb8aa3b, v115
	v_mul_f32_e32 v116, 0xbfb8aa3b, v116
	v_mul_f32_e32 v117, 0xbfb8aa3b, v117
	v_exp_f32_e32 v114, v114
	v_exp_f32_e32 v115, v115
	v_exp_f32_e32 v116, v116
	v_exp_f32_e32 v117, v117
	v_add_f32_e32 v114, 1.0, v114
	v_add_f32_e32 v115, 1.0, v115
	v_add_f32_e32 v116, 1.0, v116
	v_add_f32_e32 v117, 1.0, v117
	v_rcp_f32_e32 v114, v114
	v_rcp_f32_e32 v115, v115
	v_rcp_f32_e32 v116, v116
	v_rcp_f32_e32 v117, v117
	v_mul_f32_e32 v114, v114, v182
	v_mul_f32_e32 v115, v115, v118
	v_mul_f32_e32 v116, v116, v119
	v_mul_f32_e32 v117, v117, v120
	global_store_dwordx2 v[172:173], v[164:165], off sc1
	v_cvt_pk_bf16_f32 v118, v114, v115
	v_cvt_pk_bf16_f32 v119, v116, v117
	ds_read_b128 v[114:117], v162 offset:1024
	v_lshlrev_b32_e32 v120, 16, v178
	v_and_b32_e32 v121, 0xffff0000, v178
	global_store_dwordx2 v[122:123], v[118:119], off offset:256 sc1
	v_lshlrev_b32_e32 v118, 16, v174
	s_waitcnt lgkmcnt(0)
	v_mul_f32_e32 v114, 0xbfb8aa3b, v114
	v_mul_f32_e32 v115, 0xbfb8aa3b, v115
	v_exp_f32_e32 v114, v114
	v_exp_f32_e32 v115, v115
	v_mul_f32_e32 v116, 0xbfb8aa3b, v116
	v_exp_f32_e32 v116, v116
	v_add_f32_e32 v114, 1.0, v114
	v_add_f32_e32 v115, 1.0, v115
	v_rcp_f32_e32 v114, v114
	v_rcp_f32_e32 v115, v115
	v_mul_f32_e32 v117, 0xbfb8aa3b, v117
	v_exp_f32_e32 v117, v117
	v_mul_f32_e32 v114, v114, v120
	v_mul_f32_e32 v115, v115, v121
	v_cvt_pk_bf16_f32 v114, v114, v115
	v_add_f32_e32 v115, 1.0, v116
	v_rcp_f32_e32 v115, v115
	v_add_f32_e32 v116, 1.0, v117
	v_rcp_f32_e32 v116, v116
	v_lshlrev_b32_e32 v117, 16, v179
	v_mul_f32_e32 v115, v115, v117
	v_and_b32_e32 v117, 0xffff0000, v179
	v_mul_f32_e32 v116, v116, v117
	v_cvt_pk_bf16_f32 v115, v115, v116
	ds_write_b128 v160, v[110:113]
	ds_write_b128 v161, v[106:109]
	ds_read_b128 v[110:113], v162
	global_store_dwordx2 v[172:173], v[114:115], off offset:256 sc1
	v_add_co_u32_e32 v120, vcc, s4, v122
	s_mov_b32 s4, 0xc000
	s_waitcnt lgkmcnt(0)
; __device__ __forceinline__ unsigned cvt_pk_bf16(float lo, float hi) { unsigned r; asm volatile("v_cvt_pk_bf16_f32 %0, %1, %2" : "=v"(r) : "v"(lo), "v"(hi)); return r; }
; #define LAS __attribute__((address_space(3)))
; __device__ __forceinline__ float sigmoidf_(float x) { return __builtin_amdgcn_rcpf(1.0f + __builtin_amdgcn_exp2f(-1.4426950408889634f * x)); }
;     __device__ __forceinline__ void operator()(const pg8::f32x4 (&acc)[2][2][4][2], const Unit& u, int wr, int wc, int fr, int fq) const {
;     ...
;         for (int g = 0; g < 8; ++g) { const int ai = g >> 2, m = g & 3, rg = ai * HALF + m * 16;
;             if (g < 7) { const int rgn = ((g + 1) >> 2) * HALF + ((g + 1) & 3) * 16;
; #pragma unroll
;                 for (int bj = 0; bj < 2; ++bj)
; #pragma unroll
;                     for (int p = 0; p < 2; ++p) gn[bj][p] = *(const v2u*)(gb + (size_t)bj * 8 * MTOK * 16 + (size_t)(rgn + 8 * p) * 16); }
; #pragma unroll
;             for (int bj = 0; bj < 2; ++bj) { *(LAS pg8::f32x4*)epi_slot(W, fr, 2 * fq) = acc[ai][bj][m][0]; *(LAS pg8::f32x4*)epi_slot(W, fr, 2 * fq + 1) = acc[ai][bj][m][1];
; #pragma unroll
;                 for (int p = 0; p < 2; ++p) { const pg8::f32x4 a = *(const LAS pg8::f32x4*)epi_slot(W, 8 * p + rr, sl); const v2u gw = gc[bj][p];
;                     v2u w; w.x = cvt_pk_bf16(bflo(gw.x) * sigmoidf_(a[0]), bfhi(gw.x) * sigmoidf_(a[1])); w.y = cvt_pk_bf16(bflo(gw.y) * sigmoidf_(a[2]), bfhi(gw.y) * sigmoidf_(a[3]));
;                     *(v2u*)(ob + (size_t)(rg + 8 * p) * DM + bj * HALF) = w; } }
; #pragma unroll
;             for (int bj = 0; bj < 2; ++bj)
; #pragma unroll
;                 for (int p = 0; p < 2; ++p) gc[bj][p] = gn[bj][p]; }
	v_mul_f32_e32 v106, 0xbfb8aa3b, v110
	v_exp_f32_e32 v114, v106
	v_mul_f32_e32 v106, 0xbfb8aa3b, v111
	v_exp_f32_e32 v115, v106
	v_mul_f32_e32 v112, 0xbfb8aa3b, v112
	v_exp_f32_e32 v112, v112
	v_mul_f32_e32 v113, 0xbfb8aa3b, v113
	v_exp_f32_e32 v113, v113
	v_add_f32_e32 v114, 1.0, v114
	v_rcp_f32_e32 v114, v114
	v_add_f32_e32 v115, 1.0, v115
	v_rcp_f32_e32 v115, v115
	v_add_f32_e32 v112, 1.0, v112
	v_rcp_f32_e32 v112, v112
	v_add_f32_e32 v113, 1.0, v113
	v_rcp_f32_e32 v113, v113
	v_mul_f32_e32 v114, v114, v118
	v_and_b32_e32 v118, 0xffff0000, v174
	global_load_dwordx2 v[116:117], v[152:153], off offset:1024
	global_load_dwordx2 v[110:111], v[152:153], off offset:1280
	global_load_dwordx2 v[108:109], v[124:125], off offset:1024
	global_load_dwordx2 v[106:107], v[124:125], off offset:1280
	v_mul_f32_e32 v115, v115, v118
	v_cvt_pk_bf16_f32 v118, v114, v115
	v_lshlrev_b32_e32 v114, 16, v175
	v_mul_f32_e32 v112, v112, v114
	v_and_b32_e32 v114, 0xffff0000, v175
	v_mul_f32_e32 v113, v113, v114
	v_cvt_pk_bf16_f32 v119, v112, v113
	ds_read_b128 v[112:115], v162 offset:1024
	v_addc_co_u32_e32 v121, vcc, 0, v123, vcc
	global_store_dwordx2 v[120:121], v[118:119], off sc1
	v_lshlrev_b32_e32 v118, 16, v176
	s_waitcnt lgkmcnt(0)
	v_mul_f32_e32 v112, 0xbfb8aa3b, v112
	v_exp_f32_e32 v112, v112
	v_mul_f32_e32 v113, 0xbfb8aa3b, v113
	v_exp_f32_e32 v113, v113
	v_mul_f32_e32 v114, 0xbfb8aa3b, v114
	v_add_f32_e32 v112, 1.0, v112
	v_rcp_f32_e32 v112, v112
	v_add_f32_e32 v113, 1.0, v113
	v_rcp_f32_e32 v113, v113
	v_exp_f32_e32 v114, v114
	v_mul_f32_e32 v115, 0xbfb8aa3b, v115
	v_exp_f32_e32 v115, v115
	v_mul_f32_e32 v112, v112, v118
	v_and_b32_e32 v118, 0xffff0000, v176
	v_mul_f32_e32 v113, v113, v118
	v_cvt_pk_bf16_f32 v112, v112, v113
	v_add_f32_e32 v113, 1.0, v114
	v_rcp_f32_e32 v113, v113
	v_add_f32_e32 v114, 1.0, v115
	v_rcp_f32_e32 v114, v114
	v_lshlrev_b32_e32 v115, 16, v177
	v_mul_f32_e32 v113, v113, v115
	v_and_b32_e32 v115, 0xffff0000, v177
	v_mul_f32_e32 v114, v114, v115
	v_cvt_pk_bf16_f32 v113, v113, v114
	ds_write_b128 v160, v[102:105]
	ds_write_b128 v161, v[98:101]
	ds_read_b128 v[98:101], v162
	v_add_co_u32_e32 v102, vcc, s4, v122
	v_lshlrev_b32_e32 v104, 16, v128
	s_nop 0
	v_addc_co_u32_e32 v103, vcc, 0, v123, vcc
	s_waitcnt lgkmcnt(0)
	v_mul_f32_e32 v98, 0xbfb8aa3b, v98
	v_exp_f32_e32 v98, v98
	v_mul_f32_e32 v99, 0xbfb8aa3b, v99
	v_exp_f32_e32 v99, v99
	v_mul_f32_e32 v100, 0xbfb8aa3b, v100
	v_add_f32_e32 v98, 1.0, v98
	v_rcp_f32_e32 v98, v98
	v_add_f32_e32 v99, 1.0, v99
	v_rcp_f32_e32 v99, v99
	v_exp_f32_e32 v100, v100
	v_mul_f32_e32 v101, 0xbfb8aa3b, v101
	v_exp_f32_e32 v101, v101
	v_mul_f32_e32 v98, v98, v104
	v_and_b32_e32 v104, 0xffff0000, v128
	global_store_dwordx2 v[102:103], v[112:113], off sc1
	v_mul_f32_e32 v99, v99, v104
	v_cvt_pk_bf16_f32 v104, v98, v99
	v_add_f32_e32 v98, 1.0, v100
	v_rcp_f32_e32 v98, v98
	v_add_f32_e32 v99, 1.0, v101
	v_rcp_f32_e32 v99, v99
	v_lshlrev_b32_e32 v100, 16, v129
	v_mul_f32_e32 v98, v98, v100
	v_and_b32_e32 v100, 0xffff0000, v129
	v_mul_f32_e32 v99, v99, v100
	v_cvt_pk_bf16_f32 v105, v98, v99
	ds_read_b128 v[98:101], v162 offset:1024
	global_store_dwordx2 v[120:121], v[104:105], off offset:256 sc1
	v_lshlrev_b32_e32 v104, 16, v126
	s_mov_b32 s4, 0x10000
	s_waitcnt lgkmcnt(0)
	v_mul_f32_e32 v98, 0xbfb8aa3b, v98
	v_exp_f32_e32 v98, v98
	v_mul_f32_e32 v99, 0xbfb8aa3b, v99
	v_exp_f32_e32 v99, v99
	v_mul_f32_e32 v100, 0xbfb8aa3b, v100
	v_add_f32_e32 v98, 1.0, v98
	v_rcp_f32_e32 v98, v98
	v_add_f32_e32 v99, 1.0, v99
	v_rcp_f32_e32 v99, v99
	v_exp_f32_e32 v100, v100
	v_mul_f32_e32 v101, 0xbfb8aa3b, v101
	v_exp_f32_e32 v101, v101
	v_mul_f32_e32 v98, v98, v104
	v_and_b32_e32 v104, 0xffff0000, v126
	v_mul_f32_e32 v99, v99, v104
	v_cvt_pk_bf16_f32 v98, v98, v99
	v_add_f32_e32 v99, 1.0, v100
	v_rcp_f32_e32 v99, v99
	v_add_f32_e32 v100, 1.0, v101
	v_rcp_f32_e32 v100, v100
	v_lshlrev_b32_e32 v101, 16, v127
	v_mul_f32_e32 v99, v99, v101
	v_and_b32_e32 v101, 0xffff0000, v127
	v_mul_f32_e32 v100, v100, v101
	v_cvt_pk_bf16_f32 v99, v99, v100
	ds_write_b128 v160, v[94:97]
	ds_write_b128 v161, v[90:93]
	ds_read_b128 v[94:97], v162
	global_store_dwordx2 v[102:103], v[98:99], off offset:256 sc1
	s_waitcnt vmcnt(7)
	v_lshlrev_b32_e32 v102, 16, v116
	v_add_co_u32_e32 v104, vcc, s4, v122
	s_waitcnt lgkmcnt(0)
	v_mul_f32_e32 v90, 0xbfb8aa3b, v94
	v_exp_f32_e32 v98, v90
	v_mul_f32_e32 v90, 0xbfb8aa3b, v95
	v_exp_f32_e32 v99, v90
	v_mul_f32_e32 v96, 0xbfb8aa3b, v96
	v_exp_f32_e32 v96, v96
	v_mul_f32_e32 v97, 0xbfb8aa3b, v97
	v_exp_f32_e32 v97, v97
	v_add_f32_e32 v98, 1.0, v98
	v_rcp_f32_e32 v98, v98
	v_add_f32_e32 v99, 1.0, v99
	v_rcp_f32_e32 v99, v99
	v_add_f32_e32 v96, 1.0, v96
	v_rcp_f32_e32 v96, v96
	v_add_f32_e32 v97, 1.0, v97
	v_rcp_f32_e32 v97, v97
	v_mul_f32_e32 v98, v98, v102
	v_and_b32_e32 v102, 0xffff0000, v116
	global_load_dwordx2 v[100:101], v[152:153], off offset:1536
	global_load_dwordx2 v[94:95], v[152:153], off offset:1792
	global_load_dwordx2 v[92:93], v[124:125], off offset:1536
	global_load_dwordx2 v[90:91], v[124:125], off offset:1792
	v_mul_f32_e32 v99, v99, v102
	v_cvt_pk_bf16_f32 v102, v98, v99
	v_lshlrev_b32_e32 v98, 16, v117
	v_mul_f32_e32 v96, v96, v98
	v_and_b32_e32 v98, 0xffff0000, v117
	v_mul_f32_e32 v97, v97, v98
	v_cvt_pk_bf16_f32 v103, v96, v97
	ds_read_b128 v[96:99], v162 offset:1024
	v_addc_co_u32_e32 v105, vcc, 0, v123, vcc
	global_store_dwordx2 v[104:105], v[102:103], off sc1
	s_waitcnt vmcnt(11)
	v_lshlrev_b32_e32 v102, 16, v110
	s_waitcnt lgkmcnt(0)
; __device__ __forceinline__ unsigned cvt_pk_bf16(float lo, float hi) { unsigned r; asm volatile("v_cvt_pk_bf16_f32 %0, %1, %2" : "=v"(r) : "v"(lo), "v"(hi)); return r; }
; #define LAS __attribute__((address_space(3)))
; __device__ __forceinline__ float sigmoidf_(float x) { return __builtin_amdgcn_rcpf(1.0f + __builtin_amdgcn_exp2f(-1.4426950408889634f * x)); }
;     __device__ __forceinline__ void operator()(const pg8::f32x4 (&acc)[2][2][4][2], const Unit& u, int wr, int wc, int fr, int fq) const {
;     ...
;         for (int g = 0; g < 8; ++g) { const int ai = g >> 2, m = g & 3, rg = ai * HALF + m * 16;
;             if (g < 7) { const int rgn = ((g + 1) >> 2) * HALF + ((g + 1) & 3) * 16;
; #pragma unroll
;                 for (int bj = 0; bj < 2; ++bj)
; #pragma unroll
;                     for (int p = 0; p < 2; ++p) gn[bj][p] = *(const v2u*)(gb + (size_t)bj * 8 * MTOK * 16 + (size_t)(rgn + 8 * p) * 16); }
; #pragma unroll
;             for (int bj = 0; bj < 2; ++bj) { *(LAS pg8::f32x4*)epi_slot(W, fr, 2 * fq) = acc[ai][bj][m][0]; *(LAS pg8::f32x4*)epi_slot(W, fr, 2 * fq + 1) = acc[ai][bj][m][1];
; #pragma unroll
;                 for (int p = 0; p < 2; ++p) { const pg8::f32x4 a = *(const LAS pg8::f32x4*)epi_slot(W, 8 * p + rr, sl); const v2u gw = gc[bj][p];
;                     v2u w; w.x = cvt_pk_bf16(bflo(gw.x) * sigmoidf_(a[0]), bfhi(gw.x) * sigmoidf_(a[1])); w.y = cvt_pk_bf16(bflo(gw.y) * sigmoidf_(a[2]), bfhi(gw.y) * sigmoidf_(a[3]));
;                     *(v2u*)(ob + (size_t)(rg + 8 * p) * DM + bj * HALF) = w; } }
; #pragma unroll
;             for (int bj = 0; bj < 2; ++bj)
; #pragma unroll
;                 for (int p = 0; p < 2; ++p) gc[bj][p] = gn[bj][p]; }
	v_mul_f32_e32 v96, 0xbfb8aa3b, v96
	v_exp_f32_e32 v96, v96
	v_mul_f32_e32 v97, 0xbfb8aa3b, v97
	v_exp_f32_e32 v97, v97
	v_mul_f32_e32 v98, 0xbfb8aa3b, v98
	v_add_f32_e32 v96, 1.0, v96
	v_rcp_f32_e32 v96, v96
	v_add_f32_e32 v97, 1.0, v97
	v_rcp_f32_e32 v97, v97
	v_exp_f32_e32 v98, v98
	v_mul_f32_e32 v99, 0xbfb8aa3b, v99
	v_exp_f32_e32 v99, v99
	v_mul_f32_e32 v96, v96, v102
	v_and_b32_e32 v102, 0xffff0000, v110
	v_mul_f32_e32 v97, v97, v102
	v_cvt_pk_bf16_f32 v96, v96, v97
	v_add_f32_e32 v97, 1.0, v98
	v_rcp_f32_e32 v97, v97
	v_add_f32_e32 v98, 1.0, v99
	v_rcp_f32_e32 v98, v98
	v_lshlrev_b32_e32 v99, 16, v111
	v_mul_f32_e32 v97, v97, v99
	v_and_b32_e32 v99, 0xffff0000, v111
	v_mul_f32_e32 v98, v98, v99
	v_cvt_pk_bf16_f32 v97, v97, v98
	ds_write_b128 v160, v[86:89]
	ds_write_b128 v161, v[82:85]
	ds_read_b128 v[82:85], v162
	s_mov_b32 s4, 0x14000
	v_add_co_u32_e32 v86, vcc, s4, v122
	s_waitcnt vmcnt(10)
	v_lshlrev_b32_e32 v88, 16, v108
	s_waitcnt lgkmcnt(0)
	v_mul_f32_e32 v82, 0xbfb8aa3b, v82
	v_exp_f32_e32 v82, v82
	v_mul_f32_e32 v83, 0xbfb8aa3b, v83
	v_exp_f32_e32 v83, v83
	v_mul_f32_e32 v84, 0xbfb8aa3b, v84
	v_add_f32_e32 v82, 1.0, v82
	v_rcp_f32_e32 v82, v82
	v_add_f32_e32 v83, 1.0, v83
	v_rcp_f32_e32 v83, v83
	v_exp_f32_e32 v84, v84
	v_mul_f32_e32 v85, 0xbfb8aa3b, v85
	v_exp_f32_e32 v85, v85
	v_addc_co_u32_e32 v87, vcc, 0, v123, vcc
	v_mul_f32_e32 v82, v82, v88
	v_and_b32_e32 v88, 0xffff0000, v108
	global_store_dwordx2 v[86:87], v[96:97], off sc1
	v_mul_f32_e32 v83, v83, v88
	v_cvt_pk_bf16_f32 v88, v82, v83
	v_add_f32_e32 v82, 1.0, v84
	v_rcp_f32_e32 v82, v82
	v_add_f32_e32 v83, 1.0, v85
	v_rcp_f32_e32 v83, v83
	v_lshlrev_b32_e32 v84, 16, v109
	v_mul_f32_e32 v82, v82, v84
	v_and_b32_e32 v84, 0xffff0000, v109
	v_mul_f32_e32 v83, v83, v84
	v_cvt_pk_bf16_f32 v89, v82, v83
	ds_read_b128 v[82:85], v162 offset:1024
	global_store_dwordx2 v[104:105], v[88:89], off offset:256 sc1
	s_waitcnt vmcnt(11)
	v_lshlrev_b32_e32 v88, 16, v106
	s_movk_i32 s4, 0x1000
	s_waitcnt lgkmcnt(0)
	v_mul_f32_e32 v82, 0xbfb8aa3b, v82
	v_exp_f32_e32 v82, v82
	v_mul_f32_e32 v83, 0xbfb8aa3b, v83
	v_exp_f32_e32 v83, v83
	v_mul_f32_e32 v84, 0xbfb8aa3b, v84
	v_add_f32_e32 v82, 1.0, v82
	v_rcp_f32_e32 v82, v82
	v_add_f32_e32 v83, 1.0, v83
	v_rcp_f32_e32 v83, v83
	v_exp_f32_e32 v84, v84
	v_mul_f32_e32 v85, 0xbfb8aa3b, v85
	v_exp_f32_e32 v85, v85
	v_mul_f32_e32 v82, v82, v88
	v_and_b32_e32 v88, 0xffff0000, v106
	v_mul_f32_e32 v83, v83, v88
	v_cvt_pk_bf16_f32 v82, v82, v83
	v_add_f32_e32 v83, 1.0, v84
	v_rcp_f32_e32 v83, v83
	v_add_f32_e32 v84, 1.0, v85
	v_rcp_f32_e32 v84, v84
	v_lshlrev_b32_e32 v85, 16, v107
	v_mul_f32_e32 v83, v83, v85
	v_and_b32_e32 v85, 0xffff0000, v107
	v_mul_f32_e32 v84, v84, v85
	v_cvt_pk_bf16_f32 v83, v83, v84
	global_store_dwordx2 v[86:87], v[82:83], off offset:256 sc1
	ds_write_b128 v160, v[78:81]
	ds_write_b128 v161, v[74:77]
	ds_read_b128 v[80:83], v162
	v_add_co_u32_e32 v74, vcc, s4, v152
	s_waitcnt vmcnt(7)
	v_lshlrev_b32_e32 v88, 16, v100
	v_addc_co_u32_e32 v75, vcc, 0, v153, vcc
	s_waitcnt lgkmcnt(0)
	v_mul_f32_e32 v76, 0xbfb8aa3b, v80
	v_exp_f32_e32 v84, v76
	v_mul_f32_e32 v76, 0xbfb8aa3b, v81
	v_exp_f32_e32 v85, v76
	v_mul_f32_e32 v82, 0xbfb8aa3b, v82
	v_exp_f32_e32 v82, v82
	v_mul_f32_e32 v83, 0xbfb8aa3b, v83
	v_exp_f32_e32 v83, v83
	v_add_f32_e32 v84, 1.0, v84
	v_rcp_f32_e32 v84, v84
	v_add_f32_e32 v85, 1.0, v85
	v_rcp_f32_e32 v85, v85
	v_add_f32_e32 v82, 1.0, v82
	v_rcp_f32_e32 v82, v82
	v_add_f32_e32 v83, 1.0, v83
	v_rcp_f32_e32 v83, v83
	v_mul_f32_e32 v84, v84, v88
	v_and_b32_e32 v88, 0xffff0000, v100
	global_load_dwordx2 v[86:87], v[74:75], off
	global_load_dwordx2 v[80:81], v[74:75], off offset:256
	global_load_dwordx2 v[78:79], v[150:151], off
	global_load_dwordx2 v[76:77], v[150:151], off offset:256
	v_mul_f32_e32 v85, v85, v88
	v_cvt_pk_bf16_f32 v88, v84, v85
	v_lshlrev_b32_e32 v84, 16, v101
	v_mul_f32_e32 v82, v82, v84
	v_and_b32_e32 v84, 0xffff0000, v101
	v_mul_f32_e32 v83, v83, v84
	v_cvt_pk_bf16_f32 v89, v82, v83
	ds_read_b128 v[82:85], v162 offset:1024
	s_mov_b32 s4, 0x18000
	v_add_co_u32_e32 v96, vcc, s4, v122
	s_mov_b32 s4, 0x1c000
	s_waitcnt lgkmcnt(0)
	v_mul_f32_e32 v82, 0xbfb8aa3b, v82
	v_exp_f32_e32 v82, v82
	v_mul_f32_e32 v83, 0xbfb8aa3b, v83
	v_exp_f32_e32 v83, v83
	v_mul_f32_e32 v84, 0xbfb8aa3b, v84
	v_add_f32_e32 v82, 1.0, v82
	v_rcp_f32_e32 v82, v82
	v_add_f32_e32 v83, 1.0, v83
	v_rcp_f32_e32 v83, v83
	v_addc_co_u32_e32 v97, vcc, 0, v123, vcc
	v_exp_f32_e32 v84, v84
	v_mul_f32_e32 v85, 0xbfb8aa3b, v85
	global_store_dwordx2 v[96:97], v[88:89], off sc1
	s_waitcnt vmcnt(11)
	v_lshlrev_b32_e32 v88, 16, v94
	v_exp_f32_e32 v85, v85
	v_mul_f32_e32 v82, v82, v88
	v_and_b32_e32 v88, 0xffff0000, v94
	v_mul_f32_e32 v83, v83, v88
	v_cvt_pk_bf16_f32 v82, v82, v83
	v_add_f32_e32 v83, 1.0, v84
	v_rcp_f32_e32 v83, v83
	v_add_f32_e32 v84, 1.0, v85
	v_rcp_f32_e32 v84, v84
	v_lshlrev_b32_e32 v85, 16, v95
	v_mul_f32_e32 v83, v83, v85
	v_and_b32_e32 v85, 0xffff0000, v95
	v_mul_f32_e32 v84, v84, v85
	v_cvt_pk_bf16_f32 v83, v83, v84
	ds_write_b128 v160, v[70:73]
	ds_write_b128 v161, v[66:69]
	ds_read_b128 v[66:69], v162
	v_add_co_u32_e32 v70, vcc, s4, v122
	s_waitcnt vmcnt(10)
	v_lshlrev_b32_e32 v72, 16, v92
	v_addc_co_u32_e32 v71, vcc, 0, v123, vcc
	s_waitcnt lgkmcnt(0)
; __device__ __forceinline__ unsigned cvt_pk_bf16(float lo, float hi) { unsigned r; asm volatile("v_cvt_pk_bf16_f32 %0, %1, %2" : "=v"(r) : "v"(lo), "v"(hi)); return r; }
; #define LAS __attribute__((address_space(3)))
; __device__ __forceinline__ float sigmoidf_(float x) { return __builtin_amdgcn_rcpf(1.0f + __builtin_amdgcn_exp2f(-1.4426950408889634f * x)); }
;     __device__ __forceinline__ void operator()(const pg8::f32x4 (&acc)[2][2][4][2], const Unit& u, int wr, int wc, int fr, int fq) const {
;     ...
;         for (int g = 0; g < 8; ++g) { const int ai = g >> 2, m = g & 3, rg = ai * HALF + m * 16;
;             if (g < 7) { const int rgn = ((g + 1) >> 2) * HALF + ((g + 1) & 3) * 16;
; #pragma unroll
;                 for (int bj = 0; bj < 2; ++bj)
; #pragma unroll
;                     for (int p = 0; p < 2; ++p) gn[bj][p] = *(const v2u*)(gb + (size_t)bj * 8 * MTOK * 16 + (size_t)(rgn + 8 * p) * 16); }
; #pragma unroll
;             for (int bj = 0; bj < 2; ++bj) { *(LAS pg8::f32x4*)epi_slot(W, fr, 2 * fq) = acc[ai][bj][m][0]; *(LAS pg8::f32x4*)epi_slot(W, fr, 2 * fq + 1) = acc[ai][bj][m][1];
; #pragma unroll
;                 for (int p = 0; p < 2; ++p) { const pg8::f32x4 a = *(const LAS pg8::f32x4*)epi_slot(W, 8 * p + rr, sl); const v2u gw = gc[bj][p];
;                     v2u w; w.x = cvt_pk_bf16(bflo(gw.x) * sigmoidf_(a[0]), bfhi(gw.x) * sigmoidf_(a[1])); w.y = cvt_pk_bf16(bflo(gw.y) * sigmoidf_(a[2]), bfhi(gw.y) * sigmoidf_(a[3]));
;                     *(v2u*)(ob + (size_t)(rg + 8 * p) * DM + bj * HALF) = w; } }
; #pragma unroll
;             for (int bj = 0; bj < 2; ++bj)
; #pragma unroll
;                 for (int p = 0; p < 2; ++p) gc[bj][p] = gn[bj][p]; }
	v_mul_f32_e32 v66, 0xbfb8aa3b, v66
	v_exp_f32_e32 v66, v66
	v_mul_f32_e32 v67, 0xbfb8aa3b, v67
	v_exp_f32_e32 v67, v67
	v_mul_f32_e32 v68, 0xbfb8aa3b, v68
	v_add_f32_e32 v66, 1.0, v66
	v_rcp_f32_e32 v66, v66
	v_add_f32_e32 v67, 1.0, v67
	v_rcp_f32_e32 v67, v67
	v_exp_f32_e32 v68, v68
	v_mul_f32_e32 v69, 0xbfb8aa3b, v69
	v_exp_f32_e32 v69, v69
	v_mul_f32_e32 v66, v66, v72
	v_and_b32_e32 v72, 0xffff0000, v92
	global_store_dwordx2 v[70:71], v[82:83], off sc1
	v_mul_f32_e32 v67, v67, v72
	v_cvt_pk_bf16_f32 v72, v66, v67
	v_add_f32_e32 v66, 1.0, v68
	v_rcp_f32_e32 v66, v66
	v_add_f32_e32 v67, 1.0, v69
	v_rcp_f32_e32 v67, v67
	v_lshlrev_b32_e32 v68, 16, v93
	v_mul_f32_e32 v66, v66, v68
	v_and_b32_e32 v68, 0xffff0000, v93
	v_mul_f32_e32 v67, v67, v68
	v_cvt_pk_bf16_f32 v73, v66, v67
	ds_read_b128 v[66:69], v162 offset:1024
	global_store_dwordx2 v[96:97], v[72:73], off offset:256 sc1
	s_waitcnt vmcnt(11)
	v_lshlrev_b32_e32 v72, 16, v90
	s_mov_b32 s4, 0x40000
	s_waitcnt lgkmcnt(0)
	v_mul_f32_e32 v66, 0xbfb8aa3b, v66
	v_exp_f32_e32 v66, v66
	v_mul_f32_e32 v67, 0xbfb8aa3b, v67
	v_exp_f32_e32 v67, v67
	v_mul_f32_e32 v68, 0xbfb8aa3b, v68
	v_add_f32_e32 v66, 1.0, v66
	v_rcp_f32_e32 v66, v66
	v_add_f32_e32 v67, 1.0, v67
	v_rcp_f32_e32 v67, v67
	v_exp_f32_e32 v68, v68
	v_mul_f32_e32 v69, 0xbfb8aa3b, v69
	v_exp_f32_e32 v69, v69
	v_mul_f32_e32 v66, v66, v72
	v_and_b32_e32 v72, 0xffff0000, v90
	v_mul_f32_e32 v67, v67, v72
	v_cvt_pk_bf16_f32 v66, v66, v67
	v_add_f32_e32 v67, 1.0, v68
	v_rcp_f32_e32 v67, v67
	v_add_f32_e32 v68, 1.0, v69
	v_rcp_f32_e32 v68, v68
	v_lshlrev_b32_e32 v69, 16, v91
	v_mul_f32_e32 v67, v67, v69
	v_and_b32_e32 v69, 0xffff0000, v91
	v_mul_f32_e32 v68, v68, v69
	v_cvt_pk_bf16_f32 v67, v67, v68
	ds_write_b128 v160, v[62:65]
	ds_write_b128 v161, v[58:61]
	ds_read_b128 v[62:65], v162
	global_store_dwordx2 v[70:71], v[66:67], off offset:256 sc1
	s_waitcnt vmcnt(7)
	v_lshlrev_b32_e32 v70, 16, v86
	v_add_co_u32_e32 v72, vcc, s4, v122
	s_waitcnt lgkmcnt(0)
	v_mul_f32_e32 v58, 0xbfb8aa3b, v62
	v_exp_f32_e32 v66, v58
	v_mul_f32_e32 v58, 0xbfb8aa3b, v63
	v_exp_f32_e32 v67, v58
	v_mul_f32_e32 v64, 0xbfb8aa3b, v64
	v_exp_f32_e32 v64, v64
	v_mul_f32_e32 v65, 0xbfb8aa3b, v65
	v_exp_f32_e32 v65, v65
	v_add_f32_e32 v66, 1.0, v66
	v_rcp_f32_e32 v66, v66
	v_add_f32_e32 v67, 1.0, v67
	v_rcp_f32_e32 v67, v67
	v_add_f32_e32 v64, 1.0, v64
	v_rcp_f32_e32 v64, v64
	v_add_f32_e32 v65, 1.0, v65
	v_rcp_f32_e32 v65, v65
	v_mul_f32_e32 v66, v66, v70
	v_and_b32_e32 v70, 0xffff0000, v86
	global_load_dwordx2 v[68:69], v[74:75], off offset:512
	global_load_dwordx2 v[62:63], v[74:75], off offset:768
	global_load_dwordx2 v[60:61], v[150:151], off offset:512
	global_load_dwordx2 v[58:59], v[150:151], off offset:768
	v_mul_f32_e32 v67, v67, v70
	v_cvt_pk_bf16_f32 v70, v66, v67
	v_lshlrev_b32_e32 v66, 16, v87
	v_mul_f32_e32 v64, v64, v66
	v_and_b32_e32 v66, 0xffff0000, v87
	v_mul_f32_e32 v65, v65, v66
	v_cvt_pk_bf16_f32 v71, v64, v65
	ds_read_b128 v[64:67], v162 offset:1024
	v_addc_co_u32_e32 v73, vcc, 0, v123, vcc
	global_store_dwordx2 v[72:73], v[70:71], off sc1
	s_waitcnt vmcnt(11)
	v_lshlrev_b32_e32 v70, 16, v80
	s_waitcnt lgkmcnt(0)
	v_mul_f32_e32 v64, 0xbfb8aa3b, v64
	v_exp_f32_e32 v64, v64
	v_mul_f32_e32 v65, 0xbfb8aa3b, v65
	v_exp_f32_e32 v65, v65
	v_mul_f32_e32 v66, 0xbfb8aa3b, v66
	v_add_f32_e32 v64, 1.0, v64
	v_rcp_f32_e32 v64, v64
	v_add_f32_e32 v65, 1.0, v65
	v_rcp_f32_e32 v65, v65
	v_exp_f32_e32 v66, v66
	v_mul_f32_e32 v67, 0xbfb8aa3b, v67
	v_exp_f32_e32 v67, v67
	v_mul_f32_e32 v64, v64, v70
	v_and_b32_e32 v70, 0xffff0000, v80
	v_mul_f32_e32 v65, v65, v70
	v_cvt_pk_bf16_f32 v64, v64, v65
	v_add_f32_e32 v65, 1.0, v66
	v_rcp_f32_e32 v65, v65
	v_add_f32_e32 v66, 1.0, v67
	v_rcp_f32_e32 v66, v66
	v_lshlrev_b32_e32 v67, 16, v81
	v_mul_f32_e32 v65, v65, v67
	v_and_b32_e32 v67, 0xffff0000, v81
	v_mul_f32_e32 v66, v66, v67
	v_cvt_pk_bf16_f32 v65, v65, v66
	ds_write_b128 v160, v[54:57]
	ds_write_b128 v161, v[50:53]
	ds_read_b128 v[50:53], v162
	s_mov_b32 s4, 0x44000
	v_add_co_u32_e32 v54, vcc, s4, v122
	s_waitcnt vmcnt(10)
	v_lshlrev_b32_e32 v56, 16, v78
	s_waitcnt lgkmcnt(0)
	v_mul_f32_e32 v50, 0xbfb8aa3b, v50
	v_exp_f32_e32 v50, v50
	v_mul_f32_e32 v51, 0xbfb8aa3b, v51
	v_exp_f32_e32 v51, v51
	v_mul_f32_e32 v52, 0xbfb8aa3b, v52
	v_add_f32_e32 v50, 1.0, v50
	v_rcp_f32_e32 v50, v50
	v_add_f32_e32 v51, 1.0, v51
	v_rcp_f32_e32 v51, v51
	v_exp_f32_e32 v52, v52
	v_mul_f32_e32 v53, 0xbfb8aa3b, v53
	v_exp_f32_e32 v53, v53
	v_addc_co_u32_e32 v55, vcc, 0, v123, vcc
	v_mul_f32_e32 v50, v50, v56
	v_and_b32_e32 v56, 0xffff0000, v78
	global_store_dwordx2 v[54:55], v[64:65], off sc1
	v_mul_f32_e32 v51, v51, v56
	v_cvt_pk_bf16_f32 v56, v50, v51
	v_add_f32_e32 v50, 1.0, v52
	v_rcp_f32_e32 v50, v50
	v_add_f32_e32 v51, 1.0, v53
	v_rcp_f32_e32 v51, v51
	v_lshlrev_b32_e32 v52, 16, v79
	v_mul_f32_e32 v50, v50, v52
	v_and_b32_e32 v52, 0xffff0000, v79
	v_mul_f32_e32 v51, v51, v52
	v_cvt_pk_bf16_f32 v57, v50, v51
	ds_read_b128 v[50:53], v162 offset:1024
	global_store_dwordx2 v[72:73], v[56:57], off offset:256 sc1
	s_waitcnt vmcnt(11)
	v_lshlrev_b32_e32 v56, 16, v76
	s_mov_b32 s4, 0x48000
	s_waitcnt lgkmcnt(0)
	v_mul_f32_e32 v50, 0xbfb8aa3b, v50
	v_exp_f32_e32 v50, v50
	v_mul_f32_e32 v51, 0xbfb8aa3b, v51
	v_exp_f32_e32 v51, v51
	v_mul_f32_e32 v52, 0xbfb8aa3b, v52
	v_add_f32_e32 v50, 1.0, v50
	v_rcp_f32_e32 v50, v50
	v_add_f32_e32 v51, 1.0, v51
	v_rcp_f32_e32 v51, v51
	v_exp_f32_e32 v52, v52
	v_mul_f32_e32 v53, 0xbfb8aa3b, v53
	v_exp_f32_e32 v53, v53
	v_mul_f32_e32 v50, v50, v56
	v_and_b32_e32 v56, 0xffff0000, v76
	v_mul_f32_e32 v51, v51, v56
	v_cvt_pk_bf16_f32 v50, v50, v51
	v_add_f32_e32 v51, 1.0, v52
	v_rcp_f32_e32 v51, v51
	v_add_f32_e32 v52, 1.0, v53
	v_rcp_f32_e32 v52, v52
	v_lshlrev_b32_e32 v53, 16, v77
	v_mul_f32_e32 v51, v51, v53
	v_and_b32_e32 v53, 0xffff0000, v77
	v_mul_f32_e32 v52, v52, v53
	v_cvt_pk_bf16_f32 v51, v51, v52
	ds_write_b128 v160, v[46:49]
	ds_write_b128 v161, v[42:45]
	ds_read_b128 v[46:49], v162
	global_store_dwordx2 v[54:55], v[50:51], off offset:256 sc1
	s_waitcnt vmcnt(7)
; __device__ __forceinline__ unsigned cvt_pk_bf16(float lo, float hi) { unsigned r; asm volatile("v_cvt_pk_bf16_f32 %0, %1, %2" : "=v"(r) : "v"(lo), "v"(hi)); return r; }
; #define LAS __attribute__((address_space(3)))
; __device__ __forceinline__ float sigmoidf_(float x) { return __builtin_amdgcn_rcpf(1.0f + __builtin_amdgcn_exp2f(-1.4426950408889634f * x)); }
;     __device__ __forceinline__ void operator()(const pg8::f32x4 (&acc)[2][2][4][2], const Unit& u, int wr, int wc, int fr, int fq) const {
;     ...
;         for (int g = 0; g < 8; ++g) { const int ai = g >> 2, m = g & 3, rg = ai * HALF + m * 16;
;             if (g < 7) { const int rgn = ((g + 1) >> 2) * HALF + ((g + 1) & 3) * 16;
; #pragma unroll
;                 for (int bj = 0; bj < 2; ++bj)
; #pragma unroll
;                     for (int p = 0; p < 2; ++p) gn[bj][p] = *(const v2u*)(gb + (size_t)bj * 8 * MTOK * 16 + (size_t)(rgn + 8 * p) * 16); }
; #pragma unroll
;             for (int bj = 0; bj < 2; ++bj) { *(LAS pg8::f32x4*)epi_slot(W, fr, 2 * fq) = acc[ai][bj][m][0]; *(LAS pg8::f32x4*)epi_slot(W, fr, 2 * fq + 1) = acc[ai][bj][m][1];
; #pragma unroll
;                 for (int p = 0; p < 2; ++p) { const pg8::f32x4 a = *(const LAS pg8::f32x4*)epi_slot(W, 8 * p + rr, sl); const v2u gw = gc[bj][p];
;                     v2u w; w.x = cvt_pk_bf16(bflo(gw.x) * sigmoidf_(a[0]), bfhi(gw.x) * sigmoidf_(a[1])); w.y = cvt_pk_bf16(bflo(gw.y) * sigmoidf_(a[2]), bfhi(gw.y) * sigmoidf_(a[3]));
;                     *(v2u*)(ob + (size_t)(rg + 8 * p) * DM + bj * HALF) = w; } }
; #pragma unroll
;             for (int bj = 0; bj < 2; ++bj)
; #pragma unroll
;                 for (int p = 0; p < 2; ++p) gc[bj][p] = gn[bj][p]; }
	v_lshlrev_b32_e32 v54, 16, v68
	v_add_co_u32_e32 v56, vcc, s4, v122
	s_waitcnt lgkmcnt(0)
	v_mul_f32_e32 v42, 0xbfb8aa3b, v46
	v_exp_f32_e32 v50, v42
	v_mul_f32_e32 v42, 0xbfb8aa3b, v47
	v_exp_f32_e32 v51, v42
	v_mul_f32_e32 v48, 0xbfb8aa3b, v48
	v_exp_f32_e32 v48, v48
	v_mul_f32_e32 v49, 0xbfb8aa3b, v49
	v_exp_f32_e32 v49, v49
	v_add_f32_e32 v50, 1.0, v50
	v_rcp_f32_e32 v50, v50
	v_add_f32_e32 v51, 1.0, v51
	v_rcp_f32_e32 v51, v51
	v_add_f32_e32 v48, 1.0, v48
	v_rcp_f32_e32 v48, v48
	v_add_f32_e32 v49, 1.0, v49
	v_rcp_f32_e32 v49, v49
	v_mul_f32_e32 v50, v50, v54
	v_and_b32_e32 v54, 0xffff0000, v68
	global_load_dwordx2 v[52:53], v[74:75], off offset:1024
	global_load_dwordx2 v[46:47], v[74:75], off offset:1280
	global_load_dwordx2 v[44:45], v[150:151], off offset:1024
	global_load_dwordx2 v[42:43], v[150:151], off offset:1280
	v_mul_f32_e32 v51, v51, v54
	v_cvt_pk_bf16_f32 v54, v50, v51
	v_lshlrev_b32_e32 v50, 16, v69
	v_mul_f32_e32 v48, v48, v50
	v_and_b32_e32 v50, 0xffff0000, v69
	v_mul_f32_e32 v49, v49, v50
	v_cvt_pk_bf16_f32 v55, v48, v49
	ds_read_b128 v[48:51], v162 offset:1024
	v_addc_co_u32_e32 v57, vcc, 0, v123, vcc
	global_store_dwordx2 v[56:57], v[54:55], off sc1
	s_waitcnt vmcnt(11)
	v_lshlrev_b32_e32 v54, 16, v62
	s_waitcnt lgkmcnt(0)
	v_mul_f32_e32 v48, 0xbfb8aa3b, v48
	v_exp_f32_e32 v48, v48
	v_mul_f32_e32 v49, 0xbfb8aa3b, v49
	v_exp_f32_e32 v49, v49
	v_mul_f32_e32 v50, 0xbfb8aa3b, v50
	v_add_f32_e32 v48, 1.0, v48
	v_rcp_f32_e32 v48, v48
	v_add_f32_e32 v49, 1.0, v49
	v_rcp_f32_e32 v49, v49
	v_exp_f32_e32 v50, v50
	v_mul_f32_e32 v51, 0xbfb8aa3b, v51
	v_exp_f32_e32 v51, v51
	v_mul_f32_e32 v48, v48, v54
	v_and_b32_e32 v54, 0xffff0000, v62
	v_mul_f32_e32 v49, v49, v54
	v_cvt_pk_bf16_f32 v48, v48, v49
	v_add_f32_e32 v49, 1.0, v50
	v_rcp_f32_e32 v49, v49
	v_add_f32_e32 v50, 1.0, v51
	v_rcp_f32_e32 v50, v50
	v_lshlrev_b32_e32 v51, 16, v63
	v_mul_f32_e32 v49, v49, v51
	v_and_b32_e32 v51, 0xffff0000, v63
	v_mul_f32_e32 v50, v50, v51
	v_cvt_pk_bf16_f32 v49, v49, v50
	ds_write_b128 v160, v[38:41]
	ds_write_b128 v161, v[34:37]
	ds_read_b128 v[34:37], v162
	s_mov_b32 s4, 0x4c000
	v_add_co_u32_e32 v38, vcc, s4, v122
	s_waitcnt vmcnt(10)
	v_lshlrev_b32_e32 v40, 16, v60
	s_waitcnt lgkmcnt(0)
	v_mul_f32_e32 v34, 0xbfb8aa3b, v34
	v_exp_f32_e32 v34, v34
	v_mul_f32_e32 v35, 0xbfb8aa3b, v35
	v_exp_f32_e32 v35, v35
	v_mul_f32_e32 v36, 0xbfb8aa3b, v36
	v_add_f32_e32 v34, 1.0, v34
	v_rcp_f32_e32 v34, v34
	v_add_f32_e32 v35, 1.0, v35
	v_rcp_f32_e32 v35, v35
	v_exp_f32_e32 v36, v36
	v_mul_f32_e32 v37, 0xbfb8aa3b, v37
	v_exp_f32_e32 v37, v37
	v_addc_co_u32_e32 v39, vcc, 0, v123, vcc
	v_mul_f32_e32 v34, v34, v40
	v_and_b32_e32 v40, 0xffff0000, v60
	global_store_dwordx2 v[38:39], v[48:49], off sc1
	v_mul_f32_e32 v35, v35, v40
	v_cvt_pk_bf16_f32 v40, v34, v35
	v_add_f32_e32 v34, 1.0, v36
	v_rcp_f32_e32 v34, v34
	v_add_f32_e32 v35, 1.0, v37
	v_rcp_f32_e32 v35, v35
	v_lshlrev_b32_e32 v36, 16, v61
	v_mul_f32_e32 v34, v34, v36
	v_and_b32_e32 v36, 0xffff0000, v61
	v_mul_f32_e32 v35, v35, v36
	v_cvt_pk_bf16_f32 v41, v34, v35
	ds_read_b128 v[34:37], v162 offset:1024
	global_store_dwordx2 v[56:57], v[40:41], off offset:256 sc1
	s_waitcnt vmcnt(11)
	v_lshlrev_b32_e32 v40, 16, v58
	s_waitcnt lgkmcnt(0)
	v_mul_f32_e32 v34, 0xbfb8aa3b, v34
	v_exp_f32_e32 v34, v34
	v_mul_f32_e32 v35, 0xbfb8aa3b, v35
	v_exp_f32_e32 v35, v35
	v_mul_f32_e32 v36, 0xbfb8aa3b, v36
	v_add_f32_e32 v34, 1.0, v34
	v_rcp_f32_e32 v34, v34
	v_add_f32_e32 v35, 1.0, v35
	v_rcp_f32_e32 v35, v35
	v_exp_f32_e32 v36, v36
	v_mul_f32_e32 v37, 0xbfb8aa3b, v37
	v_exp_f32_e32 v37, v37
	v_mul_f32_e32 v34, v34, v40
	v_and_b32_e32 v40, 0xffff0000, v58
	v_mul_f32_e32 v35, v35, v40
	v_cvt_pk_bf16_f32 v34, v34, v35
	v_add_f32_e32 v35, 1.0, v36
	v_rcp_f32_e32 v35, v35
	v_add_f32_e32 v36, 1.0, v37
	v_rcp_f32_e32 v36, v36
	v_lshlrev_b32_e32 v37, 16, v59
	v_mul_f32_e32 v35, v35, v37
	v_and_b32_e32 v37, 0xffff0000, v59
	v_mul_f32_e32 v36, v36, v37
	v_cvt_pk_bf16_f32 v35, v35, v36
	ds_write_b128 v160, v[30:33]
	ds_write_b128 v161, v[26:29]
	ds_read_b128 v[30:33], v162
	global_store_dwordx2 v[38:39], v[34:35], off offset:256 sc1
	s_waitcnt vmcnt(7)
	v_lshlrev_b32_e32 v38, 16, v52
	v_add_co_u32_e32 v40, vcc, s58, v122
	s_waitcnt lgkmcnt(0)
	v_mul_f32_e32 v26, 0xbfb8aa3b, v30
	v_exp_f32_e32 v34, v26
	v_mul_f32_e32 v26, 0xbfb8aa3b, v31
	v_exp_f32_e32 v35, v26
	v_mul_f32_e32 v32, 0xbfb8aa3b, v32
	v_exp_f32_e32 v32, v32
	v_mul_f32_e32 v33, 0xbfb8aa3b, v33
	v_exp_f32_e32 v33, v33
	v_add_f32_e32 v34, 1.0, v34
	v_rcp_f32_e32 v34, v34
	v_add_f32_e32 v35, 1.0, v35
	v_rcp_f32_e32 v35, v35
	v_add_f32_e32 v32, 1.0, v32
	v_rcp_f32_e32 v32, v32
	v_add_f32_e32 v33, 1.0, v33
	v_rcp_f32_e32 v33, v33
	v_mul_f32_e32 v34, v34, v38
	v_and_b32_e32 v38, 0xffff0000, v52
	global_load_dwordx2 v[36:37], v[74:75], off offset:1536
	global_load_dwordx2 v[30:31], v[74:75], off offset:1792
	global_load_dwordx2 v[28:29], v[150:151], off offset:1536
	global_load_dwordx2 v[26:27], v[150:151], off offset:1792
	v_mul_f32_e32 v35, v35, v38
	v_cvt_pk_bf16_f32 v38, v34, v35
	v_lshlrev_b32_e32 v34, 16, v53
	v_mul_f32_e32 v32, v32, v34
	v_and_b32_e32 v34, 0xffff0000, v53
	v_mul_f32_e32 v33, v33, v34
	v_cvt_pk_bf16_f32 v39, v32, v33
	ds_read_b128 v[32:35], v162 offset:1024
	v_addc_co_u32_e32 v41, vcc, 0, v123, vcc
	global_store_dwordx2 v[40:41], v[38:39], off sc1
	s_waitcnt vmcnt(11)
	v_lshlrev_b32_e32 v38, 16, v46
	s_waitcnt lgkmcnt(0)
; __device__ __forceinline__ unsigned cvt_pk_bf16(float lo, float hi) { unsigned r; asm volatile("v_cvt_pk_bf16_f32 %0, %1, %2" : "=v"(r) : "v"(lo), "v"(hi)); return r; }
; #define LAS __attribute__((address_space(3)))
; __device__ __forceinline__ float sigmoidf_(float x) { return __builtin_amdgcn_rcpf(1.0f + __builtin_amdgcn_exp2f(-1.4426950408889634f * x)); }
; #define STAMP(i) do { } while (0)
; #define SEAM(k) do { if (IN(k) && IN((k) + 1)) { xcd_barrier(bar); xcd_barrier(bar); } } while (0)
; #define SEAM(k) do { } while (0)
;     __device__ __forceinline__ void operator()(const pg8::f32x4 (&acc)[2][2][4][2], const Unit& u, int wr, int wc, int fr, int fq) const {
;     ...
;         for (int g = 0; g < 8; ++g) { const int ai = g >> 2, m = g & 3, rg = ai * HALF + m * 16;
;             if (g < 7) { const int rgn = ((g + 1) >> 2) * HALF + ((g + 1) & 3) * 16;
; #pragma unroll
;                 for (int bj = 0; bj < 2; ++bj)
; #pragma unroll
;                     for (int p = 0; p < 2; ++p) gn[bj][p] = *(const v2u*)(gb + (size_t)bj * 8 * MTOK * 16 + (size_t)(rgn + 8 * p) * 16); }
; #pragma unroll
;             for (int bj = 0; bj < 2; ++bj) { *(LAS pg8::f32x4*)epi_slot(W, fr, 2 * fq) = acc[ai][bj][m][0]; *(LAS pg8::f32x4*)epi_slot(W, fr, 2 * fq + 1) = acc[ai][bj][m][1];
; #pragma unroll
;                 for (int p = 0; p < 2; ++p) { const pg8::f32x4 a = *(const LAS pg8::f32x4*)epi_slot(W, 8 * p + rr, sl); const v2u gw = gc[bj][p];
;                     v2u w; w.x = cvt_pk_bf16(bflo(gw.x) * sigmoidf_(a[0]), bfhi(gw.x) * sigmoidf_(a[1])); w.y = cvt_pk_bf16(bflo(gw.y) * sigmoidf_(a[2]), bfhi(gw.y) * sigmoidf_(a[3]));
;                     *(v2u*)(ob + (size_t)(rg + 8 * p) * DM + bj * HALF) = w; } }
; #pragma unroll
;             for (int bj = 0; bj < 2; ++bj)
; #pragma unroll
;                 for (int p = 0; p < 2; ++p) gc[bj][p] = gn[bj][p]; }
; __global__ void __launch_bounds__(NWAVES * 64, 2) mk_fwd(Args args) {
;     ...
;         pg8::Gemm g{GY, (const bf16*)(F.ws + WS_WGLU), MTOK, S5W, S5W}; pg8::StaticOrder S; S.init(MTOK, S5W, F.G, F.bid);
;         EpiGlu E{GY, MIX, F.lds + EPI_SCR};
;         STAMP(13);
;         pg8::gemm_phase<EpiGlu, pg8::StaticOrder, true, true, true>(F.lds, g, S, E);
;         __syncthreads();
;         STAMP(14);
;         hgC_loop(F, (unsigned*)(F.ws + WS_CTL) + CW_QUEUE);
;         STAMP(15);
;     } SEAM(4);
	v_mul_f32_e32 v32, 0xbfb8aa3b, v32
	v_exp_f32_e32 v32, v32
	v_mul_f32_e32 v33, 0xbfb8aa3b, v33
	v_exp_f32_e32 v33, v33
	v_mul_f32_e32 v34, 0xbfb8aa3b, v34
	v_add_f32_e32 v32, 1.0, v32
	v_rcp_f32_e32 v32, v32
	v_add_f32_e32 v33, 1.0, v33
	v_rcp_f32_e32 v33, v33
	v_exp_f32_e32 v34, v34
	v_mul_f32_e32 v35, 0xbfb8aa3b, v35
	v_exp_f32_e32 v35, v35
	v_mul_f32_e32 v32, v32, v38
	v_and_b32_e32 v38, 0xffff0000, v46
	v_mul_f32_e32 v33, v33, v38
	v_cvt_pk_bf16_f32 v32, v32, v33
	v_add_f32_e32 v33, 1.0, v34
	v_rcp_f32_e32 v33, v33
	v_add_f32_e32 v34, 1.0, v35
	v_rcp_f32_e32 v34, v34
	v_lshlrev_b32_e32 v35, 16, v47
	v_mul_f32_e32 v33, v33, v35
	v_and_b32_e32 v35, 0xffff0000, v47
	v_mul_f32_e32 v34, v34, v35
	v_cvt_pk_bf16_f32 v33, v33, v34
	ds_write_b128 v160, v[22:25]
	ds_write_b128 v161, v[18:21]
	ds_read_b128 v[18:21], v162
	v_add_co_u32_e32 v22, vcc, s59, v122
	s_waitcnt vmcnt(10)
	v_lshlrev_b32_e32 v24, 16, v44
	v_addc_co_u32_e32 v23, vcc, 0, v123, vcc
	s_waitcnt lgkmcnt(0)
	v_mul_f32_e32 v18, 0xbfb8aa3b, v18
	v_exp_f32_e32 v18, v18
	v_mul_f32_e32 v19, 0xbfb8aa3b, v19
	v_exp_f32_e32 v19, v19
	v_mul_f32_e32 v20, 0xbfb8aa3b, v20
	v_add_f32_e32 v18, 1.0, v18
	v_rcp_f32_e32 v18, v18
	v_add_f32_e32 v19, 1.0, v19
	v_rcp_f32_e32 v19, v19
	v_exp_f32_e32 v20, v20
	v_mul_f32_e32 v21, 0xbfb8aa3b, v21
	v_exp_f32_e32 v21, v21
	v_mul_f32_e32 v18, v18, v24
	v_and_b32_e32 v24, 0xffff0000, v44
	global_store_dwordx2 v[22:23], v[32:33], off sc1
	v_mul_f32_e32 v19, v19, v24
	v_cvt_pk_bf16_f32 v24, v18, v19
	v_add_f32_e32 v18, 1.0, v20
	v_rcp_f32_e32 v18, v18
	v_add_f32_e32 v19, 1.0, v21
	v_rcp_f32_e32 v19, v19
	v_lshlrev_b32_e32 v20, 16, v45
	v_mul_f32_e32 v18, v18, v20
	v_and_b32_e32 v20, 0xffff0000, v45
	v_mul_f32_e32 v19, v19, v20
	v_cvt_pk_bf16_f32 v25, v18, v19
	ds_read_b128 v[18:21], v162 offset:1024
	global_store_dwordx2 v[40:41], v[24:25], off offset:256 sc1
	s_waitcnt vmcnt(11)
	v_lshlrev_b32_e32 v24, 16, v42
	s_waitcnt lgkmcnt(0)
	v_mul_f32_e32 v18, 0xbfb8aa3b, v18
	v_exp_f32_e32 v18, v18
	v_mul_f32_e32 v19, 0xbfb8aa3b, v19
	v_exp_f32_e32 v19, v19
	v_mul_f32_e32 v20, 0xbfb8aa3b, v20
	v_add_f32_e32 v18, 1.0, v18
	v_rcp_f32_e32 v18, v18
	v_add_f32_e32 v19, 1.0, v19
	v_rcp_f32_e32 v19, v19
	v_exp_f32_e32 v20, v20
	v_mul_f32_e32 v21, 0xbfb8aa3b, v21
	v_exp_f32_e32 v21, v21
	v_mul_f32_e32 v18, v18, v24
	v_and_b32_e32 v24, 0xffff0000, v42
	v_mul_f32_e32 v19, v19, v24
	v_cvt_pk_bf16_f32 v18, v18, v19
	v_add_f32_e32 v19, 1.0, v20
	v_rcp_f32_e32 v19, v19
	v_add_f32_e32 v20, 1.0, v21
	v_rcp_f32_e32 v20, v20
	v_lshlrev_b32_e32 v21, 16, v43
	v_mul_f32_e32 v19, v19, v21
	v_and_b32_e32 v21, 0xffff0000, v43
	v_mul_f32_e32 v20, v20, v21
	v_cvt_pk_bf16_f32 v19, v19, v20
	ds_write_b128 v160, v[14:17]
	ds_write_b128 v161, v[10:13]
	ds_read_b128 v[10:13], v162
	s_waitcnt vmcnt(6)
	v_lshlrev_b32_e32 v14, 16, v36
	global_store_dwordx2 v[22:23], v[18:19], off offset:256 sc1
	v_add_co_u32_e32 v16, vcc, s60, v122
	s_waitcnt lgkmcnt(0)
	v_mul_f32_e32 v10, 0xbfb8aa3b, v10
	v_exp_f32_e32 v10, v10
	v_mul_f32_e32 v11, 0xbfb8aa3b, v11
	v_exp_f32_e32 v11, v11
	v_mul_f32_e32 v12, 0xbfb8aa3b, v12
	v_add_f32_e32 v10, 1.0, v10
	v_rcp_f32_e32 v10, v10
	v_add_f32_e32 v11, 1.0, v11
	v_rcp_f32_e32 v11, v11
	v_exp_f32_e32 v12, v12
	v_mul_f32_e32 v13, 0xbfb8aa3b, v13
	v_exp_f32_e32 v13, v13
	v_mul_f32_e32 v10, v10, v14
	v_and_b32_e32 v14, 0xffff0000, v36
	v_mul_f32_e32 v11, v11, v14
	v_cvt_pk_bf16_f32 v14, v10, v11
	v_add_f32_e32 v10, 1.0, v12
	v_rcp_f32_e32 v10, v10
	v_add_f32_e32 v11, 1.0, v13
	v_rcp_f32_e32 v11, v11
	v_lshlrev_b32_e32 v12, 16, v37
	v_mul_f32_e32 v10, v10, v12
	v_and_b32_e32 v12, 0xffff0000, v37
	v_mul_f32_e32 v11, v11, v12
	v_cvt_pk_bf16_f32 v15, v10, v11
	ds_read_b128 v[10:13], v162 offset:1024
	v_addc_co_u32_e32 v17, vcc, 0, v123, vcc
	global_store_dwordx2 v[16:17], v[14:15], off sc1
	s_waitcnt vmcnt(7)
	v_lshlrev_b32_e32 v14, 16, v30
	s_waitcnt lgkmcnt(0)
	v_mul_f32_e32 v10, 0xbfb8aa3b, v10
	v_exp_f32_e32 v10, v10
	v_mul_f32_e32 v11, 0xbfb8aa3b, v11
	v_exp_f32_e32 v11, v11
	v_mul_f32_e32 v12, 0xbfb8aa3b, v12
	v_add_f32_e32 v10, 1.0, v10
	v_rcp_f32_e32 v10, v10
	v_add_f32_e32 v11, 1.0, v11
	v_rcp_f32_e32 v11, v11
	v_exp_f32_e32 v12, v12
	v_mul_f32_e32 v13, 0xbfb8aa3b, v13
	v_exp_f32_e32 v13, v13
	v_mul_f32_e32 v10, v10, v14
	v_and_b32_e32 v14, 0xffff0000, v30
	v_mul_f32_e32 v11, v11, v14
	v_cvt_pk_bf16_f32 v10, v10, v11
	v_add_f32_e32 v11, 1.0, v12
	v_rcp_f32_e32 v11, v11
	v_add_f32_e32 v12, 1.0, v13
	v_rcp_f32_e32 v12, v12
	v_lshlrev_b32_e32 v13, 16, v31
	v_mul_f32_e32 v11, v11, v13
	v_and_b32_e32 v13, 0xffff0000, v31
	v_mul_f32_e32 v12, v12, v13
	v_cvt_pk_bf16_f32 v11, v11, v12
	ds_write_b128 v160, v[6:9]
	ds_write_b128 v161, v[2:5]
	ds_read_b128 v[2:5], v162
	v_add_co_u32_e32 v6, vcc, s61, v122
	s_waitcnt vmcnt(6)
	v_lshlrev_b32_e32 v8, 16, v28
	v_addc_co_u32_e32 v7, vcc, 0, v123, vcc
	s_waitcnt lgkmcnt(0)
	v_mul_f32_e32 v2, 0xbfb8aa3b, v2
	v_exp_f32_e32 v2, v2
	v_mul_f32_e32 v3, 0xbfb8aa3b, v3
	v_exp_f32_e32 v3, v3
	v_mul_f32_e32 v4, 0xbfb8aa3b, v4
	v_add_f32_e32 v2, 1.0, v2
	v_rcp_f32_e32 v2, v2
	v_add_f32_e32 v3, 1.0, v3
	v_rcp_f32_e32 v3, v3
	v_exp_f32_e32 v4, v4
	v_mul_f32_e32 v5, 0xbfb8aa3b, v5
	v_exp_f32_e32 v5, v5
	v_mul_f32_e32 v2, v2, v8
	v_and_b32_e32 v8, 0xffff0000, v28
	global_store_dwordx2 v[6:7], v[10:11], off sc1
	v_mul_f32_e32 v3, v3, v8
	v_cvt_pk_bf16_f32 v8, v2, v3
	v_add_f32_e32 v2, 1.0, v4
	v_rcp_f32_e32 v2, v2
	v_add_f32_e32 v3, 1.0, v5
	v_rcp_f32_e32 v3, v3
	v_lshlrev_b32_e32 v4, 16, v29
	v_mul_f32_e32 v2, v2, v4
	v_and_b32_e32 v4, 0xffff0000, v29
	v_mul_f32_e32 v3, v3, v4
	v_cvt_pk_bf16_f32 v9, v2, v3
	ds_read_b128 v[2:5], v162 offset:1024
	global_store_dwordx2 v[16:17], v[8:9], off offset:256 sc1
	s_waitcnt vmcnt(7)
	v_lshlrev_b32_e32 v8, 16, v26
	s_andn2_b64 vcc, exec, s[0:1]
	s_mov_b64 s[0:1], -1
	s_waitcnt lgkmcnt(0)
	v_mul_f32_e32 v2, 0xbfb8aa3b, v2
	v_exp_f32_e32 v2, v2
	v_mul_f32_e32 v3, 0xbfb8aa3b, v3
	v_exp_f32_e32 v3, v3
	v_mul_f32_e32 v4, 0xbfb8aa3b, v4
	v_add_f32_e32 v2, 1.0, v2
	v_rcp_f32_e32 v2, v2
	v_add_f32_e32 v3, 1.0, v3
	v_rcp_f32_e32 v3, v3
	v_exp_f32_e32 v4, v4
	v_mul_f32_e32 v5, 0xbfb8aa3b, v5
	v_exp_f32_e32 v5, v5
	v_mul_f32_e32 v2, v2, v8
	v_and_b32_e32 v8, 0xffff0000, v26
	v_mul_f32_e32 v3, v3, v8
	v_cvt_pk_bf16_f32 v2, v2, v3
	v_add_f32_e32 v3, 1.0, v4
	v_rcp_f32_e32 v3, v3
	v_add_f32_e32 v4, 1.0, v5
	v_rcp_f32_e32 v4, v4
	v_lshlrev_b32_e32 v5, 16, v27
	v_mul_f32_e32 v3, v3, v5
	v_and_b32_e32 v5, 0xffff0000, v27
	v_mul_f32_e32 v4, v4, v5
	v_cvt_pk_bf16_f32 v3, v3, v4
	global_store_dwordx2 v[6:7], v[2:3], off offset:256 sc1
	s_cbranch_vccnz .LBB0_673
	s_andn2_b64 vcc, exec, s[10:11]
	s_cbranch_vccnz .LBB0_672
	s_barrier
	s_branch .LBB0_672
